# asm guide 7.4: all per-segment s_setprio flips of the GEMM mainloops deleted, one static s_setprio 1 for waves 4-7 at kernel entry
# speedup vs baseline: 1.0180x; 1.0055x over previous
; #define LAS __attribute__((address_space(3)))
; __global__ void __launch_bounds__(NWAVES * 64, 2) fwd_kernel(Args args) {
;     extern __shared__ __attribute__((aligned(16))) unsigned char lds_raw[];
;     LAS unsigned char* lds = (LAS unsigned char*)lds_raw;
;     cg::grid_group grid = cg::this_grid();
;     const int tid = threadIdx.x, lane = tid & 63, wave = __builtin_amdgcn_readfirstlane(tid >> 6);
;     const int G = gridDim.x, bid = blockIdx.x;
;     const int gw = bid * NWAVES + wave, NGW = G * NWAVES;
;     const bool split_roles = (G == 256);
_Z10fwd_kernel4Args:
	s_load_dwordx8 s[56:63], s[0:1], 0x60
	s_load_dwordx8 s[4:11], s[0:1], 0x40
	s_load_dword s52, s[0:1], 0x80
	v_and_b32_e32 v195, 0x3ff, v0
	s_mov_b32 s48, s2
	s_mov_b32 s100, 0
	v_readfirstlane_b32 s24, v195
	s_waitcnt lgkmcnt(0)
	s_nop 3
	s_lshr_b32 s101, s24, 8
	s_cmp_lg_u32 s101, 0
	s_cbranch_scc0 .Lprio_done
	s_setprio 1
.Lprio_done:
	v_writelane_b32 v243, s4, 0
	v_cmp_eq_u32_e64 s[54:55], 0, v195
	s_nop 0
	v_writelane_b32 v243, s5, 1
	v_writelane_b32 v243, s6, 2
	v_writelane_b32 v243, s7, 3
	v_writelane_b32 v243, s8, 4
	v_writelane_b32 v243, s9, 5
	v_writelane_b32 v243, s10, 6
	v_writelane_b32 v243, s11, 7
	s_add_u32 s4, s0, 0x78
	s_addc_u32 s5, s1, 0
	s_and_saveexec_b64 s[2:3], s[54:55]
	s_cbranch_execz .LBB0_2
	s_add_i32 s6, 0, 0x23fc0
	v_mov_b32_e32 v1, 0
	v_mov_b32_e32 v2, s6
	s_add_i32 s6, 0, 0x23fc4
	ds_write_b32 v2, v1
	v_mov_b32_e32 v2, s6
	ds_write_b32 v2, v1

; #define PG8_STAGE(bufoff, gbase, voff) do { _Pragma("unroll") for (int _i = 0; _i < 2; ++_i) \
;         __builtin_amdgcn_global_load_lds((const unsigned*)((const char*)(gbase) + (voff)[_i]), (LAS unsigned*)(lds + (bufoff) + ldsw + _i * 8192), 16, 0, 0); } while (0)
; #define PG8_LDA(dst, b, h) do { _Pragma("unroll") for (int m = 0; m < 4; ++m) _Pragma("unroll") for (int k = 0; k < 2; ++k) dst[m][k] = *(const LAS bf16x8*)(lds + PG8_SA(b, h) + aoff + m * 2048 + k * 1024); } while (0)
; #define PG8_LDB(dst, b, h) do { _Pragma("unroll") for (int n = 0; n < 2; ++n) _Pragma("unroll") for (int k = 0; k < 2; ++k) dst[n][k] = *(const LAS bf16x8*)(lds + PG8_SB(b, h) + boff + n * 2048 + k * 1024); } while (0)
; #define PG8_MMA(ai, bj, At, Bt) do { __builtin_amdgcn_s_setprio(1); _Pragma("unroll") for (int m = 0; m < 4; ++m) _Pragma("unroll") for (int n = 0; n < 2; ++n) _Pragma("unroll") for (int k = 0; k < 2; ++k) \
;         acc[ai][bj][m][n] = __builtin_amdgcn_mfma_f32_16x16x32_bf16(Bt[n][k], At[m][k], acc[ai][bj][m][n], 0, 0, 0); __builtin_amdgcn_s_setprio(0); } while (0)
; #define PG8_WAIT_V(n) asm volatile("s_waitcnt vmcnt(" #n ")" ::: "memory")
; #define PG8_WAIT_L(n) asm volatile("s_waitcnt lgkmcnt(" #n ")" ::: "memory")
; #define PG8_BAR __builtin_amdgcn_s_barrier()
; #define PG8_SCHED __builtin_amdgcn_sched_barrier(0)
; template <class Epi, bool ALIGN_EPI, bool SP2 = PG8_SP2_DEFAULT>
; __device__ __forceinline__ void gemm_phase(LAS unsigned char* lds, const Gemm g, const StaticOrder& S, const Epi& E) {
;     ...
;             PG8_LDB(B0, 0, 0); PG8_LDB(B1, 0, 1); PG8_SCHED; PG8_LDA(At, 0, 0); PG8_STAGE(PG8_SA(1, 1), a1 + hstepA, voffA);
;             PG8_WAIT_V(8); PG8_WAIT_L(0); PG8_BAR; PG8_MMA(0, 0, At, B0); PG8_MMA(0, 1, At, B1); PG8_BAR; PG8_SCHED;
;             PG8_LDA(At, 0, 1); PG8_STAGE(PG8_SB(0, 0), b2, voffB); PG8_STAGE(PG8_SB(0, 1), b2 + hstepB, voffB); PG8_STAGE(PG8_SA(0, 0), a2, voffA);
.LBB0_250:
	ds_read_b128 v[150:153], v147
	ds_read_b128 v[154:157], v147 offset:1024
	ds_read_b128 v[158:161], v147 offset:2048
	ds_read_b128 v[162:165], v147 offset:3072
	ds_read_b128 v[166:169], v148
	ds_read_b128 v[170:173], v148 offset:1024
	ds_read_b128 v[174:177], v148 offset:2048
	ds_read_b128 v[178:181], v148 offset:3072
	s_add_u32 s20, s18, 0xfff00080
	s_addc_u32 s21, s19, -1
	s_cmp_eq_u32 s44, 60
	s_cselect_b32 s23, s13, s21
	s_cselect_b32 s22, s40, s20
	s_cselect_b32 s21, s11, s43
	s_cselect_b32 s20, s41, s42
	v_lshl_add_u64 v[206:207], s[18:19], 0, v[136:137]
	s_add_i32 m0, s9, 0xc000
	ds_read_b128 v[182:185], v149
	ds_read_b128 v[186:189], v149 offset:1024
	ds_read_b128 v[190:193], v149 offset:2048
	ds_read_b128 v[198:201], v149 offset:3072
	ds_read_b128 v[202:205], v149 offset:4096
	ds_read_b128 v[216:219], v149 offset:5120
	ds_read_b128 v[220:223], v149 offset:6144
	ds_read_b128 v[224:227], v149 offset:7168
	global_load_lds_dwordx4 v[206:207], off
	v_lshl_add_u64 v[206:207], s[18:19], 0, v[138:139]
	s_add_i32 m0, s9, 0xe000
	s_nop 0
	global_load_lds_dwordx4 v[206:207], off
	s_waitcnt vmcnt(8)
	s_waitcnt lgkmcnt(0)
	s_barrier
	s_waitcnt lgkmcnt(0)
	v_mfma_f32_16x16x32_bf16 v[124:127], v[150:153], v[182:185], v[124:127]
	v_mfma_f32_16x16x32_bf16 v[120:123], v[158:161], v[182:185], v[120:123]
	v_mfma_f32_16x16x32_bf16 v[116:119], v[150:153], v[190:193], v[116:119]
	v_mfma_f32_16x16x32_bf16 v[112:115], v[158:161], v[190:193], v[112:115]
	v_mfma_f32_16x16x32_bf16 v[100:103], v[150:153], v[202:205], v[100:103]
	v_mfma_f32_16x16x32_bf16 v[96:99], v[158:161], v[202:205], v[96:99]
	v_mfma_f32_16x16x32_bf16 v[84:87], v[150:153], v[220:223], v[84:87]
	v_mfma_f32_16x16x32_bf16 v[80:83], v[158:161], v[220:223], v[80:83]
	v_mfma_f32_16x16x32_bf16 v[124:127], v[154:157], v[186:189], v[124:127]
	v_mfma_f32_16x16x32_bf16 v[120:123], v[162:165], v[186:189], v[120:123]
	v_mfma_f32_16x16x32_bf16 v[116:119], v[154:157], v[198:201], v[116:119]
	v_mfma_f32_16x16x32_bf16 v[112:115], v[162:165], v[198:201], v[112:115]
	v_mfma_f32_16x16x32_bf16 v[100:103], v[154:157], v[216:219], v[100:103]
	v_mfma_f32_16x16x32_bf16 v[96:99], v[162:165], v[216:219], v[96:99]
	v_mfma_f32_16x16x32_bf16 v[84:87], v[154:157], v[224:227], v[84:87]
	v_mfma_f32_16x16x32_bf16 v[80:83], v[162:165], v[224:227], v[80:83]
	v_mfma_f32_16x16x32_bf16 v[108:111], v[166:169], v[182:185], v[108:111]
	v_mfma_f32_16x16x32_bf16 v[104:107], v[174:177], v[182:185], v[104:107]
	v_mfma_f32_16x16x32_bf16 v[92:95], v[166:169], v[190:193], v[92:95]
	v_mfma_f32_16x16x32_bf16 v[88:91], v[174:177], v[190:193], v[88:91]
	v_mfma_f32_16x16x32_bf16 v[76:79], v[166:169], v[202:205], v[76:79]
	v_mfma_f32_16x16x32_bf16 v[72:75], v[174:177], v[202:205], v[72:75]
	v_mfma_f32_16x16x32_bf16 v[68:71], v[166:169], v[220:223], v[68:71]
	v_mfma_f32_16x16x32_bf16 v[64:67], v[174:177], v[220:223], v[64:67]
	v_mfma_f32_16x16x32_bf16 v[108:111], v[170:173], v[186:189], v[108:111]
	v_mfma_f32_16x16x32_bf16 v[104:107], v[178:181], v[186:189], v[104:107]
	v_mfma_f32_16x16x32_bf16 v[92:95], v[170:173], v[198:201], v[92:95]
	v_mfma_f32_16x16x32_bf16 v[88:91], v[178:181], v[198:201], v[88:91]
	v_mfma_f32_16x16x32_bf16 v[76:79], v[170:173], v[216:219], v[76:79]
	v_mfma_f32_16x16x32_bf16 v[72:75], v[178:181], v[216:219], v[72:75]
	v_mfma_f32_16x16x32_bf16 v[68:71], v[170:173], v[224:227], v[68:71]
	v_mfma_f32_16x16x32_bf16 v[64:67], v[178:181], v[224:227], v[64:67]
	s_barrier
	s_add_i32 s45, s36, s24
	v_lshl_add_u64 v[206:207], s[20:21], 0, v[132:133]
	s_mov_b32 m0, s45
	ds_read_b128 v[182:185], v149 offset:16384
	ds_read_b128 v[186:189], v149 offset:17408
	ds_read_b128 v[190:193], v149 offset:18432
	ds_read_b128 v[198:201], v149 offset:19456
	ds_read_b128 v[202:205], v149 offset:20480
	ds_read_b128 v[216:219], v149 offset:21504
	ds_read_b128 v[220:223], v149 offset:22528
	ds_read_b128 v[224:227], v149 offset:23552
	global_load_lds_dwordx4 v[206:207], off
	s_add_i32 m0, s45, 0x2000
	s_add_u32 s46, s20, 0x100000
	v_lshl_add_u64 v[210:211], s[20:21], 0, v[128:129]
	s_addc_u32 s47, s21, 0
	s_add_i32 s45, s37, s24
	global_load_lds_dwordx4 v[210:211], off
	v_lshl_add_u64 v[228:229], s[46:47], 0, v[132:133]
	s_mov_b32 m0, s45
	v_lshl_add_u64 v[230:231], s[22:23], 0, v[130:131]
	global_load_lds_dwordx4 v[228:229], off
	v_lshl_add_u64 v[228:229], s[46:47], 0, v[128:129]
	s_add_i32 m0, s45, 0x2000
	s_nop 0
	global_load_lds_dwordx4 v[228:229], off
	v_lshl_add_u64 v[228:229], s[22:23], 0, v[134:135]
	s_mov_b32 m0, s9
	s_nop 0
	global_load_lds_dwordx4 v[228:229], off
	s_mov_b32 m0, s27
	s_nop 0
	global_load_lds_dwordx4 v[230:231], off
	s_waitcnt vmcnt(8)
	s_waitcnt lgkmcnt(0)
	s_barrier
; #define PG8_STAGE(bufoff, gbase, voff) do { _Pragma("unroll") for (int _i = 0; _i < 2; ++_i) \
;         __builtin_amdgcn_global_load_lds((const unsigned*)((const char*)(gbase) + (voff)[_i]), (LAS unsigned*)(lds + (bufoff) + ldsw + _i * 8192), 16, 0, 0); } while (0)
; #define PG8_LDA(dst, b, h) do { _Pragma("unroll") for (int m = 0; m < 4; ++m) _Pragma("unroll") for (int k = 0; k < 2; ++k) dst[m][k] = *(const LAS bf16x8*)(lds + PG8_SA(b, h) + aoff + m * 2048 + k * 1024); } while (0)
; #define PG8_LDB(dst, b, h) do { _Pragma("unroll") for (int n = 0; n < 2; ++n) _Pragma("unroll") for (int k = 0; k < 2; ++k) dst[n][k] = *(const LAS bf16x8*)(lds + PG8_SB(b, h) + boff + n * 2048 + k * 1024); } while (0)
; #define PG8_MMA(ai, bj, At, Bt) do { __builtin_amdgcn_s_setprio(1); _Pragma("unroll") for (int m = 0; m < 4; ++m) _Pragma("unroll") for (int n = 0; n < 2; ++n) _Pragma("unroll") for (int k = 0; k < 2; ++k) \
;         acc[ai][bj][m][n] = __builtin_amdgcn_mfma_f32_16x16x32_bf16(Bt[n][k], At[m][k], acc[ai][bj][m][n], 0, 0, 0); __builtin_amdgcn_s_setprio(0); } while (0)
; #define PG8_WAIT_V(n) asm volatile("s_waitcnt vmcnt(" #n ")" ::: "memory")
; #define PG8_WAIT_L(n) asm volatile("s_waitcnt lgkmcnt(" #n ")" ::: "memory")
; #define PG8_BAR __builtin_amdgcn_s_barrier()
; #define PG8_SCHED __builtin_amdgcn_sched_barrier(0)
; template <class Epi, bool ALIGN_EPI, bool SP2 = PG8_SP2_DEFAULT>
; __device__ __forceinline__ void gemm_phase(LAS unsigned char* lds, const Gemm g, const StaticOrder& S, const Epi& E) {
;     ...
;             PG8_WAIT_V(8); PG8_WAIT_L(0); PG8_BAR; PG8_MMA(1, 0, At, B0); PG8_MMA(1, 1, At, B1); PG8_BAR; PG8_SCHED;
;             PG8_LDB(B0, 1, 0); PG8_LDB(B1, 1, 1); PG8_SCHED; PG8_LDA(At, 1, 0); PG8_STAGE(PG8_SA(0, 1), a2 + hstepA, voffA);
;             PG8_WAIT_V(8); PG8_WAIT_L(0); PG8_BAR; PG8_MMA(0, 0, At, B0); PG8_MMA(0, 1, At, B1); PG8_BAR; PG8_SCHED;
	s_waitcnt lgkmcnt(0)
	v_mfma_f32_16x16x32_bf16 v[60:63], v[150:153], v[182:185], v[60:63]
	v_mfma_f32_16x16x32_bf16 v[56:59], v[158:161], v[182:185], v[56:59]
	v_mfma_f32_16x16x32_bf16 v[52:55], v[150:153], v[190:193], v[52:55]
	v_mfma_f32_16x16x32_bf16 v[48:51], v[158:161], v[190:193], v[48:51]
	v_mfma_f32_16x16x32_bf16 v[36:39], v[150:153], v[202:205], v[36:39]
	v_mfma_f32_16x16x32_bf16 v[32:35], v[158:161], v[202:205], v[32:35]
	v_mfma_f32_16x16x32_bf16 v[20:23], v[150:153], v[220:223], v[20:23]
	v_mfma_f32_16x16x32_bf16 v[16:19], v[158:161], v[220:223], v[16:19]
	v_mfma_f32_16x16x32_bf16 v[60:63], v[154:157], v[186:189], v[60:63]
	v_mfma_f32_16x16x32_bf16 v[56:59], v[162:165], v[186:189], v[56:59]
	v_mfma_f32_16x16x32_bf16 v[52:55], v[154:157], v[198:201], v[52:55]
	v_mfma_f32_16x16x32_bf16 v[48:51], v[162:165], v[198:201], v[48:51]
	v_mfma_f32_16x16x32_bf16 v[36:39], v[154:157], v[216:219], v[36:39]
	v_mfma_f32_16x16x32_bf16 v[32:35], v[162:165], v[216:219], v[32:35]
	v_mfma_f32_16x16x32_bf16 v[20:23], v[154:157], v[224:227], v[20:23]
	v_mfma_f32_16x16x32_bf16 v[16:19], v[162:165], v[224:227], v[16:19]
	v_mfma_f32_16x16x32_bf16 v[44:47], v[166:169], v[182:185], v[44:47]
	v_mfma_f32_16x16x32_bf16 v[40:43], v[174:177], v[182:185], v[40:43]
	v_mfma_f32_16x16x32_bf16 v[28:31], v[166:169], v[190:193], v[28:31]
	v_mfma_f32_16x16x32_bf16 v[24:27], v[174:177], v[190:193], v[24:27]
	v_mfma_f32_16x16x32_bf16 v[12:15], v[166:169], v[202:205], v[12:15]
	v_mfma_f32_16x16x32_bf16 v[8:11], v[174:177], v[202:205], v[8:11]
	v_mfma_f32_16x16x32_bf16 v[4:7], v[166:169], v[220:223], v[4:7]
	v_mfma_f32_16x16x32_bf16 v[0:3], v[174:177], v[220:223], v[0:3]
	v_mfma_f32_16x16x32_bf16 v[44:47], v[170:173], v[186:189], v[44:47]
	v_mfma_f32_16x16x32_bf16 v[40:43], v[178:181], v[186:189], v[40:43]
	v_mfma_f32_16x16x32_bf16 v[28:31], v[170:173], v[198:201], v[28:31]
	v_mfma_f32_16x16x32_bf16 v[24:27], v[178:181], v[198:201], v[24:27]
	v_mfma_f32_16x16x32_bf16 v[12:15], v[170:173], v[216:219], v[12:15]
	v_mfma_f32_16x16x32_bf16 v[8:11], v[178:181], v[216:219], v[8:11]
	v_mfma_f32_16x16x32_bf16 v[4:7], v[170:173], v[224:227], v[4:7]
	v_mfma_f32_16x16x32_bf16 v[0:3], v[178:181], v[224:227], v[0:3]
	s_barrier
	s_add_i32 s45, 0, 0x18000
	s_add_i32 s46, 0, 0x1c000
	v_add_u32_e32 v162, s45, v145
	v_add_u32_e32 v178, s46, v145
	ds_read_b128 v[150:153], v162
	ds_read_b128 v[154:157], v162 offset:1024
	ds_read_b128 v[158:161], v162 offset:2048
	ds_read_b128 v[162:165], v162 offset:3072
	ds_read_b128 v[166:169], v178
	ds_read_b128 v[170:173], v178 offset:1024
	ds_read_b128 v[174:177], v178 offset:2048
	ds_read_b128 v[178:181], v178 offset:3072
	s_add_u32 s22, s22, 0x100000
	s_addc_u32 s23, s23, 0
	s_mov_b32 m0, s28
	v_lshl_add_u64 v[232:233], s[22:23], 0, v[134:135]
	ds_read_b128 v[182:185], v149 offset:32768
	ds_read_b128 v[186:189], v149 offset:33792
	ds_read_b128 v[190:193], v149 offset:34816
	ds_read_b128 v[198:201], v149 offset:35840
	ds_read_b128 v[202:205], v149 offset:36864
	ds_read_b128 v[216:219], v149 offset:37888
	ds_read_b128 v[220:223], v149 offset:38912
	ds_read_b128 v[224:227], v149 offset:39936
	global_load_lds_dwordx4 v[232:233], off
	v_lshl_add_u64 v[232:233], s[22:23], 0, v[130:131]
	s_mov_b32 m0, s29
	s_nop 0
	global_load_lds_dwordx4 v[232:233], off
	s_waitcnt vmcnt(8)
	s_waitcnt lgkmcnt(0)
	s_barrier
	s_waitcnt lgkmcnt(0)
	v_mfma_f32_16x16x32_bf16 v[124:127], v[150:153], v[182:185], v[124:127]
	v_mfma_f32_16x16x32_bf16 v[120:123], v[158:161], v[182:185], v[120:123]
	v_mfma_f32_16x16x32_bf16 v[116:119], v[150:153], v[190:193], v[116:119]
	v_mfma_f32_16x16x32_bf16 v[112:115], v[158:161], v[190:193], v[112:115]
	v_mfma_f32_16x16x32_bf16 v[100:103], v[150:153], v[202:205], v[100:103]
	v_mfma_f32_16x16x32_bf16 v[96:99], v[158:161], v[202:205], v[96:99]
	v_mfma_f32_16x16x32_bf16 v[84:87], v[150:153], v[220:223], v[84:87]
	v_mfma_f32_16x16x32_bf16 v[80:83], v[158:161], v[220:223], v[80:83]
	v_mfma_f32_16x16x32_bf16 v[124:127], v[154:157], v[186:189], v[124:127]
	v_mfma_f32_16x16x32_bf16 v[120:123], v[162:165], v[186:189], v[120:123]
	v_mfma_f32_16x16x32_bf16 v[116:119], v[154:157], v[198:201], v[116:119]
	v_mfma_f32_16x16x32_bf16 v[112:115], v[162:165], v[198:201], v[112:115]
	v_mfma_f32_16x16x32_bf16 v[100:103], v[154:157], v[216:219], v[100:103]
	v_mfma_f32_16x16x32_bf16 v[96:99], v[162:165], v[216:219], v[96:99]
	v_mfma_f32_16x16x32_bf16 v[84:87], v[154:157], v[224:227], v[84:87]
	v_mfma_f32_16x16x32_bf16 v[80:83], v[162:165], v[224:227], v[80:83]
	v_mfma_f32_16x16x32_bf16 v[108:111], v[166:169], v[182:185], v[108:111]
	v_mfma_f32_16x16x32_bf16 v[104:107], v[174:177], v[182:185], v[104:107]
	v_mfma_f32_16x16x32_bf16 v[92:95], v[166:169], v[190:193], v[92:95]
	v_mfma_f32_16x16x32_bf16 v[88:91], v[174:177], v[190:193], v[88:91]
	v_mfma_f32_16x16x32_bf16 v[76:79], v[166:169], v[202:205], v[76:79]
	v_mfma_f32_16x16x32_bf16 v[72:75], v[174:177], v[202:205], v[72:75]
	v_mfma_f32_16x16x32_bf16 v[68:71], v[166:169], v[220:223], v[68:71]
	v_mfma_f32_16x16x32_bf16 v[64:67], v[174:177], v[220:223], v[64:67]
	v_mfma_f32_16x16x32_bf16 v[108:111], v[170:173], v[186:189], v[108:111]
	v_mfma_f32_16x16x32_bf16 v[104:107], v[178:181], v[186:189], v[104:107]
	v_mfma_f32_16x16x32_bf16 v[92:95], v[170:173], v[198:201], v[92:95]
	v_mfma_f32_16x16x32_bf16 v[88:91], v[178:181], v[198:201], v[88:91]
	v_mfma_f32_16x16x32_bf16 v[76:79], v[170:173], v[216:219], v[76:79]
	v_mfma_f32_16x16x32_bf16 v[72:75], v[178:181], v[216:219], v[72:75]
	v_mfma_f32_16x16x32_bf16 v[68:71], v[170:173], v[224:227], v[68:71]
	v_mfma_f32_16x16x32_bf16 v[64:67], v[178:181], v[224:227], v[64:67]
	s_barrier
; #define PG8_STAGE(bufoff, gbase, voff) do { _Pragma("unroll") for (int _i = 0; _i < 2; ++_i) \
;         __builtin_amdgcn_global_load_lds((const unsigned*)((const char*)(gbase) + (voff)[_i]), (LAS unsigned*)(lds + (bufoff) + ldsw + _i * 8192), 16, 0, 0); } while (0)
; #define PG8_LDA(dst, b, h) do { _Pragma("unroll") for (int m = 0; m < 4; ++m) _Pragma("unroll") for (int k = 0; k < 2; ++k) dst[m][k] = *(const LAS bf16x8*)(lds + PG8_SA(b, h) + aoff + m * 2048 + k * 1024); } while (0)
; #define PG8_MMA(ai, bj, At, Bt) do { __builtin_amdgcn_s_setprio(1); _Pragma("unroll") for (int m = 0; m < 4; ++m) _Pragma("unroll") for (int n = 0; n < 2; ++n) _Pragma("unroll") for (int k = 0; k < 2; ++k) \
;         acc[ai][bj][m][n] = __builtin_amdgcn_mfma_f32_16x16x32_bf16(Bt[n][k], At[m][k], acc[ai][bj][m][n], 0, 0, 0); __builtin_amdgcn_s_setprio(0); } while (0)
; #define PG8_WAIT_V(n) asm volatile("s_waitcnt vmcnt(" #n ")" ::: "memory")
; #define PG8_WAIT_L(n) asm volatile("s_waitcnt lgkmcnt(" #n ")" ::: "memory")
; #define PG8_BAR __builtin_amdgcn_s_barrier()
; #define PG8_SCHED __builtin_amdgcn_sched_barrier(0)
; template <class Epi, bool ALIGN_EPI, bool SP2 = PG8_SP2_DEFAULT>
; __device__ __forceinline__ void gemm_phase(LAS unsigned char* lds, const Gemm g, const StaticOrder& S, const Epi& E) {
;     ...
;         for (int t = 0; t < nt; t += 2) {
;             const bool last = (t == nt - 2);
;             const char* a1 = cA + (size_t)(t + 1) * kstep;
;             const char* a2 = last ? nA : cA + (size_t)(t + 2) * kstep; const char* b2 = last ? nB : cB + (size_t)(t + 2) * kstep;
;             const char* a3 = a2 + kstep; const char* b3 = b2 + kstep;
;     ...
;             PG8_LDA(At, 1, 1); PG8_STAGE(PG8_SB(1, 0), b3, voffB); PG8_STAGE(PG8_SB(1, 1), b3 + hstepB, voffB); PG8_STAGE(PG8_SA(1, 0), a3, voffA);
;             PG8_WAIT_V(8); PG8_WAIT_L(0); PG8_BAR; PG8_MMA(1, 0, At, B0); PG8_MMA(1, 1, At, B1); PG8_BAR; PG8_SCHED;
	s_add_i32 s22, s45, s24
	v_lshl_add_u64 v[206:207], v[206:207], 0, s[4:5]
	s_mov_b32 m0, s22
	ds_read_b128 v[182:185], v149 offset:49152
	ds_read_b128 v[186:189], v149 offset:50176
	ds_read_b128 v[190:193], v149 offset:51200
	ds_read_b128 v[198:201], v149 offset:52224
	ds_read_b128 v[202:205], v149 offset:53248
	ds_read_b128 v[216:219], v149 offset:54272
	ds_read_b128 v[220:223], v149 offset:55296
	ds_read_b128 v[224:227], v149 offset:56320
	global_load_lds_dwordx4 v[206:207], off
	s_add_i32 m0, s22, 0x2000
	s_add_u32 s20, s20, 0x100080
	v_lshl_add_u64 v[206:207], v[210:211], 0, s[4:5]
	s_addc_u32 s21, s21, 0
	s_add_i32 s22, s46, s24
	global_load_lds_dwordx4 v[206:207], off
	v_lshl_add_u64 v[206:207], s[20:21], 0, v[132:133]
	s_mov_b32 m0, s22
	s_nop 0
	global_load_lds_dwordx4 v[206:207], off
	v_lshl_add_u64 v[206:207], s[20:21], 0, v[128:129]
	s_add_i32 m0, s22, 0x2000
	s_nop 0
	global_load_lds_dwordx4 v[206:207], off
	v_lshl_add_u64 v[206:207], v[228:229], 0, s[4:5]
	s_mov_b32 m0, s33
	s_nop 0
	global_load_lds_dwordx4 v[206:207], off
	v_lshl_add_u64 v[206:207], v[230:231], 0, s[4:5]
	s_mov_b32 m0, s34
	s_nop 0
	global_load_lds_dwordx4 v[206:207], off
	s_waitcnt vmcnt(8)
	s_waitcnt lgkmcnt(0)
	s_barrier
	s_waitcnt lgkmcnt(0)
	v_mfma_f32_16x16x32_bf16 v[60:63], v[150:153], v[182:185], v[60:63]
	v_mfma_f32_16x16x32_bf16 v[56:59], v[158:161], v[182:185], v[56:59]
	v_mfma_f32_16x16x32_bf16 v[52:55], v[150:153], v[190:193], v[52:55]
	v_mfma_f32_16x16x32_bf16 v[48:51], v[158:161], v[190:193], v[48:51]
	v_mfma_f32_16x16x32_bf16 v[36:39], v[150:153], v[202:205], v[36:39]
	v_mfma_f32_16x16x32_bf16 v[32:35], v[158:161], v[202:205], v[32:35]
	v_mfma_f32_16x16x32_bf16 v[20:23], v[150:153], v[220:223], v[20:23]
	v_mfma_f32_16x16x32_bf16 v[16:19], v[158:161], v[220:223], v[16:19]
	v_mfma_f32_16x16x32_bf16 v[60:63], v[154:157], v[186:189], v[60:63]
	v_mfma_f32_16x16x32_bf16 v[56:59], v[162:165], v[186:189], v[56:59]
	v_mfma_f32_16x16x32_bf16 v[52:55], v[154:157], v[198:201], v[52:55]
	v_mfma_f32_16x16x32_bf16 v[48:51], v[162:165], v[198:201], v[48:51]
	v_mfma_f32_16x16x32_bf16 v[36:39], v[154:157], v[216:219], v[36:39]
	v_mfma_f32_16x16x32_bf16 v[32:35], v[162:165], v[216:219], v[32:35]
	v_mfma_f32_16x16x32_bf16 v[20:23], v[154:157], v[224:227], v[20:23]
	v_mfma_f32_16x16x32_bf16 v[16:19], v[162:165], v[224:227], v[16:19]
	v_mfma_f32_16x16x32_bf16 v[44:47], v[166:169], v[182:185], v[44:47]
	v_mfma_f32_16x16x32_bf16 v[40:43], v[174:177], v[182:185], v[40:43]
	v_mfma_f32_16x16x32_bf16 v[28:31], v[166:169], v[190:193], v[28:31]
	v_mfma_f32_16x16x32_bf16 v[24:27], v[174:177], v[190:193], v[24:27]
	v_mfma_f32_16x16x32_bf16 v[12:15], v[166:169], v[202:205], v[12:15]
	v_mfma_f32_16x16x32_bf16 v[8:11], v[174:177], v[202:205], v[8:11]
	v_mfma_f32_16x16x32_bf16 v[4:7], v[166:169], v[220:223], v[4:7]
	v_mfma_f32_16x16x32_bf16 v[0:3], v[174:177], v[220:223], v[0:3]
	v_mfma_f32_16x16x32_bf16 v[44:47], v[170:173], v[186:189], v[44:47]
	v_mfma_f32_16x16x32_bf16 v[40:43], v[178:181], v[186:189], v[40:43]
	v_mfma_f32_16x16x32_bf16 v[28:31], v[170:173], v[198:201], v[28:31]
	v_mfma_f32_16x16x32_bf16 v[24:27], v[178:181], v[198:201], v[24:27]
	v_mfma_f32_16x16x32_bf16 v[12:15], v[170:173], v[216:219], v[12:15]
	v_mfma_f32_16x16x32_bf16 v[8:11], v[178:181], v[216:219], v[8:11]
	v_mfma_f32_16x16x32_bf16 v[4:7], v[170:173], v[224:227], v[4:7]
	v_mfma_f32_16x16x32_bf16 v[0:3], v[178:181], v[224:227], v[0:3]
	s_barrier
	s_add_i32 s44, s44, 2
	s_add_u32 s18, s18, 0x100
	s_addc_u32 s19, s19, 0
	s_add_u32 s42, s42, 0x100
	s_addc_u32 s43, s43, 0
	s_cmp_gt_u32 s44, 61
	s_cbranch_scc0 .LBB0_250
	s_and_b64 vcc, exec, s[6:7]
	s_cbranch_vccz .LBB0_253
	s_barrier

; #define PG8_STAGE(bufoff, gbase, voff) do { _Pragma("unroll") for (int _i = 0; _i < 2; ++_i) \
;         __builtin_amdgcn_global_load_lds((const unsigned*)((const char*)(gbase) + (voff)[_i]), (LAS unsigned*)(lds + (bufoff) + ldsw + _i * 8192), 16, 0, 0); } while (0)
; #define PG8_LDA(dst, b, h) do { _Pragma("unroll") for (int m = 0; m < 4; ++m) _Pragma("unroll") for (int k = 0; k < 2; ++k) dst[m][k] = *(const LAS bf16x8*)(lds + PG8_SA(b, h) + aoff + m * 2048 + k * 1024); } while (0)
; #define PG8_LDB(dst, b, h) do { _Pragma("unroll") for (int n = 0; n < 2; ++n) _Pragma("unroll") for (int k = 0; k < 2; ++k) dst[n][k] = *(const LAS bf16x8*)(lds + PG8_SB(b, h) + boff + n * 2048 + k * 1024); } while (0)
; #define PG8_MMA(ai, bj, At, Bt) do { __builtin_amdgcn_s_setprio(1); _Pragma("unroll") for (int m = 0; m < 4; ++m) _Pragma("unroll") for (int n = 0; n < 2; ++n) _Pragma("unroll") for (int k = 0; k < 2; ++k) \
;         acc[ai][bj][m][n] = __builtin_amdgcn_mfma_f32_16x16x32_bf16(Bt[n][k], At[m][k], acc[ai][bj][m][n], 0, 0, 0); __builtin_amdgcn_s_setprio(0); } while (0)
; #define PG8_WAIT_V(n) asm volatile("s_waitcnt vmcnt(" #n ")" ::: "memory")
; #define PG8_WAIT_L(n) asm volatile("s_waitcnt lgkmcnt(" #n ")" ::: "memory")
; #define PG8_BAR __builtin_amdgcn_s_barrier()
; #define PG8_SCHED __builtin_amdgcn_sched_barrier(0)
; template <class Epi, bool ALIGN_EPI, bool SP2 = PG8_SP2_DEFAULT>
; __device__ __forceinline__ void gemm_phase(LAS unsigned char* lds, const Gemm g, const StaticOrder& S, const Epi& E) {
;     ...
;             PG8_LDB(B0, 0, 0); PG8_LDB(B1, 0, 1); PG8_SCHED; PG8_LDA(At, 0, 0); PG8_STAGE(PG8_SA(1, 1), a1 + hstepA, voffA);
;             PG8_WAIT_V(8); PG8_WAIT_L(0); PG8_BAR; PG8_MMA(0, 0, At, B0); PG8_MMA(0, 1, At, B1); PG8_BAR; PG8_SCHED;
;             PG8_LDA(At, 0, 1); PG8_STAGE(PG8_SB(0, 0), b2, voffB); PG8_STAGE(PG8_SB(0, 1), b2 + hstepB, voffB); PG8_STAGE(PG8_SA(0, 0), a2, voffA);
.LBB0_428:
	ds_read_b128 v[128:131], v165
	ds_read_b128 v[132:135], v165 offset:1024
	ds_read_b128 v[136:139], v165 offset:2048
	ds_read_b128 v[140:143], v165 offset:3072
	ds_read_b128 v[168:171], v166
	ds_read_b128 v[172:175], v166 offset:1024
	ds_read_b128 v[176:179], v166 offset:2048
	ds_read_b128 v[180:183], v166 offset:3072
	s_add_u32 s24, s22, 0xfffe0080
	s_addc_u32 s25, s23, -1
	s_cmp_eq_u32 s51, 4
	s_cselect_b32 s27, s15, s25
	s_cselect_b32 s26, s47, s24
	s_cselect_b32 s25, s13, s50
	s_cselect_b32 s24, s48, s49
	v_lshl_add_u64 v[160:161], s[22:23], 0, v[152:153]
	s_add_i32 m0, s21, 0xc000
	ds_read_b128 v[184:187], v167
	ds_read_b128 v[188:191], v167 offset:1024
	ds_read_b128 v[198:201], v167 offset:2048
	ds_read_b128 v[202:205], v167 offset:3072
	ds_read_b128 v[216:219], v167 offset:4096
	ds_read_b128 v[220:223], v167 offset:5120
	ds_read_b128 v[224:227], v167 offset:6144
	ds_read_b128 v[228:231], v167 offset:7168
	global_load_lds_dwordx4 v[160:161], off
	v_lshl_add_u64 v[160:161], s[22:23], 0, v[154:155]
	s_add_i32 m0, s21, 0xe000
	s_nop 0
	global_load_lds_dwordx4 v[160:161], off
	s_waitcnt vmcnt(8)
	s_waitcnt lgkmcnt(0)
	s_barrier
	s_waitcnt lgkmcnt(0)
	v_mfma_f32_16x16x32_bf16 v[124:127], v[128:131], v[184:187], v[124:127]
	v_mfma_f32_16x16x32_bf16 v[120:123], v[136:139], v[184:187], v[120:123]
	v_mfma_f32_16x16x32_bf16 v[116:119], v[128:131], v[198:201], v[116:119]
	v_mfma_f32_16x16x32_bf16 v[112:115], v[136:139], v[198:201], v[112:115]
	v_mfma_f32_16x16x32_bf16 v[108:111], v[128:131], v[216:219], v[108:111]
	v_mfma_f32_16x16x32_bf16 v[100:103], v[136:139], v[216:219], v[100:103]
	v_mfma_f32_16x16x32_bf16 v[80:83], v[128:131], v[224:227], v[80:83]
	v_mfma_f32_16x16x32_bf16 v[72:75], v[136:139], v[224:227], v[72:75]
	v_mfma_f32_16x16x32_bf16 v[124:127], v[132:135], v[188:191], v[124:127]
	v_mfma_f32_16x16x32_bf16 v[120:123], v[140:143], v[188:191], v[120:123]
	v_mfma_f32_16x16x32_bf16 v[116:119], v[132:135], v[202:205], v[116:119]
	v_mfma_f32_16x16x32_bf16 v[112:115], v[140:143], v[202:205], v[112:115]
	v_mfma_f32_16x16x32_bf16 v[108:111], v[132:135], v[220:223], v[108:111]
	v_mfma_f32_16x16x32_bf16 v[100:103], v[140:143], v[220:223], v[100:103]
	v_mfma_f32_16x16x32_bf16 v[80:83], v[132:135], v[228:231], v[80:83]
	v_mfma_f32_16x16x32_bf16 v[72:75], v[140:143], v[228:231], v[72:75]
	v_mfma_f32_16x16x32_bf16 v[104:107], v[168:171], v[184:187], v[104:107]
	v_mfma_f32_16x16x32_bf16 v[96:99], v[176:179], v[184:187], v[96:99]
	v_mfma_f32_16x16x32_bf16 v[92:95], v[168:171], v[198:201], v[92:95]
	v_mfma_f32_16x16x32_bf16 v[88:91], v[176:179], v[198:201], v[88:91]
	v_mfma_f32_16x16x32_bf16 v[84:87], v[168:171], v[216:219], v[84:87]
	v_mfma_f32_16x16x32_bf16 v[76:79], v[176:179], v[216:219], v[76:79]
	v_mfma_f32_16x16x32_bf16 v[68:71], v[168:171], v[224:227], v[68:71]
	v_mfma_f32_16x16x32_bf16 v[64:67], v[176:179], v[224:227], v[64:67]
	v_mfma_f32_16x16x32_bf16 v[104:107], v[172:175], v[188:191], v[104:107]
	v_mfma_f32_16x16x32_bf16 v[96:99], v[180:183], v[188:191], v[96:99]
	v_mfma_f32_16x16x32_bf16 v[92:95], v[172:175], v[202:205], v[92:95]
	v_mfma_f32_16x16x32_bf16 v[88:91], v[180:183], v[202:205], v[88:91]
	v_mfma_f32_16x16x32_bf16 v[84:87], v[172:175], v[220:223], v[84:87]
	v_mfma_f32_16x16x32_bf16 v[76:79], v[180:183], v[220:223], v[76:79]
	v_mfma_f32_16x16x32_bf16 v[68:71], v[172:175], v[228:231], v[68:71]
	v_mfma_f32_16x16x32_bf16 v[64:67], v[180:183], v[228:231], v[64:67]
	s_barrier
	s_add_i32 s52, s40, s29
	v_lshl_add_u64 v[160:161], s[24:25], 0, v[146:147]
	s_mov_b32 m0, s52
	ds_read_b128 v[184:187], v167 offset:16384
	ds_read_b128 v[188:191], v167 offset:17408
	ds_read_b128 v[198:201], v167 offset:18432
	ds_read_b128 v[202:205], v167 offset:19456
	ds_read_b128 v[216:219], v167 offset:20480
	ds_read_b128 v[220:223], v167 offset:21504
	ds_read_b128 v[224:227], v167 offset:22528
	ds_read_b128 v[228:231], v167 offset:23552
	global_load_lds_dwordx4 v[160:161], off
	s_add_i32 m0, s52, 0x2000
	s_add_u32 s52, s24, 0x20000
	v_lshl_add_u64 v[192:193], s[24:25], 0, v[150:151]
	s_addc_u32 s53, s25, 0
	s_add_i32 s54, s41, s29
	global_load_lds_dwordx4 v[192:193], off
	v_lshl_add_u64 v[206:207], s[52:53], 0, v[146:147]
	s_mov_b32 m0, s54
	v_lshl_add_u64 v[210:211], s[26:27], 0, v[148:149]
	global_load_lds_dwordx4 v[206:207], off
	v_lshl_add_u64 v[206:207], s[52:53], 0, v[150:151]
	s_add_i32 m0, s54, 0x2000
	s_nop 0
	global_load_lds_dwordx4 v[206:207], off
	v_lshl_add_u64 v[206:207], s[26:27], 0, v[144:145]
	s_mov_b32 m0, s21
	s_nop 0
	global_load_lds_dwordx4 v[206:207], off
	s_mov_b32 m0, s30
	s_nop 0
	global_load_lds_dwordx4 v[210:211], off
	s_waitcnt vmcnt(8)
	s_waitcnt lgkmcnt(0)
	s_barrier
; #define PG8_STAGE(bufoff, gbase, voff) do { _Pragma("unroll") for (int _i = 0; _i < 2; ++_i) \
;         __builtin_amdgcn_global_load_lds((const unsigned*)((const char*)(gbase) + (voff)[_i]), (LAS unsigned*)(lds + (bufoff) + ldsw + _i * 8192), 16, 0, 0); } while (0)
; #define PG8_LDA(dst, b, h) do { _Pragma("unroll") for (int m = 0; m < 4; ++m) _Pragma("unroll") for (int k = 0; k < 2; ++k) dst[m][k] = *(const LAS bf16x8*)(lds + PG8_SA(b, h) + aoff + m * 2048 + k * 1024); } while (0)
; #define PG8_LDB(dst, b, h) do { _Pragma("unroll") for (int n = 0; n < 2; ++n) _Pragma("unroll") for (int k = 0; k < 2; ++k) dst[n][k] = *(const LAS bf16x8*)(lds + PG8_SB(b, h) + boff + n * 2048 + k * 1024); } while (0)
; #define PG8_MMA(ai, bj, At, Bt) do { __builtin_amdgcn_s_setprio(1); _Pragma("unroll") for (int m = 0; m < 4; ++m) _Pragma("unroll") for (int n = 0; n < 2; ++n) _Pragma("unroll") for (int k = 0; k < 2; ++k) \
;         acc[ai][bj][m][n] = __builtin_amdgcn_mfma_f32_16x16x32_bf16(Bt[n][k], At[m][k], acc[ai][bj][m][n], 0, 0, 0); __builtin_amdgcn_s_setprio(0); } while (0)
; #define PG8_WAIT_V(n) asm volatile("s_waitcnt vmcnt(" #n ")" ::: "memory")
; #define PG8_WAIT_L(n) asm volatile("s_waitcnt lgkmcnt(" #n ")" ::: "memory")
; #define PG8_BAR __builtin_amdgcn_s_barrier()
; #define PG8_SCHED __builtin_amdgcn_sched_barrier(0)
; template <class Epi, bool ALIGN_EPI, bool SP2 = PG8_SP2_DEFAULT>
; __device__ __forceinline__ void gemm_phase(LAS unsigned char* lds, const Gemm g, const StaticOrder& S, const Epi& E) {
;     ...
;             PG8_WAIT_V(8); PG8_WAIT_L(0); PG8_BAR; PG8_MMA(1, 0, At, B0); PG8_MMA(1, 1, At, B1); PG8_BAR; PG8_SCHED;
;             PG8_LDB(B0, 1, 0); PG8_LDB(B1, 1, 1); PG8_SCHED; PG8_LDA(At, 1, 0); PG8_STAGE(PG8_SA(0, 1), a2 + hstepA, voffA);
;             PG8_WAIT_V(8); PG8_WAIT_L(0); PG8_BAR; PG8_MMA(0, 0, At, B0); PG8_MMA(0, 1, At, B1); PG8_BAR; PG8_SCHED;
	s_waitcnt lgkmcnt(0)
	v_mfma_f32_16x16x32_bf16 v[60:63], v[128:131], v[184:187], v[60:63]
	v_mfma_f32_16x16x32_bf16 v[56:59], v[136:139], v[184:187], v[56:59]
	v_mfma_f32_16x16x32_bf16 v[52:55], v[128:131], v[198:201], v[52:55]
	v_mfma_f32_16x16x32_bf16 v[44:47], v[136:139], v[198:201], v[44:47]
	v_mfma_f32_16x16x32_bf16 v[36:39], v[128:131], v[216:219], v[36:39]
	v_mfma_f32_16x16x32_bf16 v[28:31], v[136:139], v[216:219], v[28:31]
	v_mfma_f32_16x16x32_bf16 v[20:23], v[128:131], v[224:227], v[20:23]
	v_mfma_f32_16x16x32_bf16 v[12:15], v[136:139], v[224:227], v[12:15]
	v_mfma_f32_16x16x32_bf16 v[60:63], v[132:135], v[188:191], v[60:63]
	v_mfma_f32_16x16x32_bf16 v[56:59], v[140:143], v[188:191], v[56:59]
	v_mfma_f32_16x16x32_bf16 v[52:55], v[132:135], v[202:205], v[52:55]
	v_mfma_f32_16x16x32_bf16 v[44:47], v[140:143], v[202:205], v[44:47]
	v_mfma_f32_16x16x32_bf16 v[36:39], v[132:135], v[220:223], v[36:39]
	v_mfma_f32_16x16x32_bf16 v[28:31], v[140:143], v[220:223], v[28:31]
	v_mfma_f32_16x16x32_bf16 v[20:23], v[132:135], v[228:231], v[20:23]
	v_mfma_f32_16x16x32_bf16 v[12:15], v[140:143], v[228:231], v[12:15]
	v_mfma_f32_16x16x32_bf16 v[48:51], v[168:171], v[184:187], v[48:51]
	v_mfma_f32_16x16x32_bf16 v[40:43], v[176:179], v[184:187], v[40:43]
	v_mfma_f32_16x16x32_bf16 v[32:35], v[168:171], v[198:201], v[32:35]
	v_mfma_f32_16x16x32_bf16 v[24:27], v[176:179], v[198:201], v[24:27]
	v_mfma_f32_16x16x32_bf16 v[16:19], v[168:171], v[216:219], v[16:19]
	v_mfma_f32_16x16x32_bf16 v[8:11], v[176:179], v[216:219], v[8:11]
	v_mfma_f32_16x16x32_bf16 v[4:7], v[168:171], v[224:227], v[4:7]
	v_mfma_f32_16x16x32_bf16 v[0:3], v[176:179], v[224:227], v[0:3]
	v_mfma_f32_16x16x32_bf16 v[48:51], v[172:175], v[188:191], v[48:51]
	v_mfma_f32_16x16x32_bf16 v[40:43], v[180:183], v[188:191], v[40:43]
	v_mfma_f32_16x16x32_bf16 v[32:35], v[172:175], v[202:205], v[32:35]
	v_mfma_f32_16x16x32_bf16 v[24:27], v[180:183], v[202:205], v[24:27]
	v_mfma_f32_16x16x32_bf16 v[16:19], v[172:175], v[220:223], v[16:19]
	v_mfma_f32_16x16x32_bf16 v[8:11], v[180:183], v[220:223], v[8:11]
	v_mfma_f32_16x16x32_bf16 v[4:7], v[172:175], v[228:231], v[4:7]
	v_mfma_f32_16x16x32_bf16 v[0:3], v[180:183], v[228:231], v[0:3]
	s_barrier
	s_add_i32 s52, 0, 0x18000
	s_add_i32 s53, 0, 0x1c000
	v_add_u32_e32 v140, s52, v163
	v_add_u32_e32 v180, s53, v163
	ds_read_b128 v[128:131], v140
	ds_read_b128 v[132:135], v140 offset:1024
	ds_read_b128 v[136:139], v140 offset:2048
	ds_read_b128 v[140:143], v140 offset:3072
	ds_read_b128 v[168:171], v180
	ds_read_b128 v[172:175], v180 offset:1024
	ds_read_b128 v[176:179], v180 offset:2048
	ds_read_b128 v[180:183], v180 offset:3072
	s_add_u32 s26, s26, 0x20000
	s_addc_u32 s27, s27, 0
	s_mov_b32 m0, s31
	v_lshl_add_u64 v[232:233], s[26:27], 0, v[144:145]
	ds_read_b128 v[184:187], v167 offset:32768
	ds_read_b128 v[188:191], v167 offset:33792
	ds_read_b128 v[198:201], v167 offset:34816
	ds_read_b128 v[202:205], v167 offset:35840
	ds_read_b128 v[216:219], v167 offset:36864
	ds_read_b128 v[220:223], v167 offset:37888
	ds_read_b128 v[224:227], v167 offset:38912
	ds_read_b128 v[228:231], v167 offset:39936
	global_load_lds_dwordx4 v[232:233], off
	v_lshl_add_u64 v[232:233], s[26:27], 0, v[148:149]
	s_mov_b32 m0, s34
	s_nop 0
	global_load_lds_dwordx4 v[232:233], off
	s_waitcnt vmcnt(8)
	s_waitcnt lgkmcnt(0)
	s_barrier
	s_waitcnt lgkmcnt(0)
	v_mfma_f32_16x16x32_bf16 v[124:127], v[128:131], v[184:187], v[124:127]
	v_mfma_f32_16x16x32_bf16 v[120:123], v[136:139], v[184:187], v[120:123]
	v_mfma_f32_16x16x32_bf16 v[116:119], v[128:131], v[198:201], v[116:119]
	v_mfma_f32_16x16x32_bf16 v[112:115], v[136:139], v[198:201], v[112:115]
	v_mfma_f32_16x16x32_bf16 v[108:111], v[128:131], v[216:219], v[108:111]
	v_mfma_f32_16x16x32_bf16 v[100:103], v[136:139], v[216:219], v[100:103]
	v_mfma_f32_16x16x32_bf16 v[80:83], v[128:131], v[224:227], v[80:83]
	v_mfma_f32_16x16x32_bf16 v[72:75], v[136:139], v[224:227], v[72:75]
	v_mfma_f32_16x16x32_bf16 v[124:127], v[132:135], v[188:191], v[124:127]
	v_mfma_f32_16x16x32_bf16 v[120:123], v[140:143], v[188:191], v[120:123]
	v_mfma_f32_16x16x32_bf16 v[116:119], v[132:135], v[202:205], v[116:119]
	v_mfma_f32_16x16x32_bf16 v[112:115], v[140:143], v[202:205], v[112:115]
	v_mfma_f32_16x16x32_bf16 v[108:111], v[132:135], v[220:223], v[108:111]
	v_mfma_f32_16x16x32_bf16 v[100:103], v[140:143], v[220:223], v[100:103]
	v_mfma_f32_16x16x32_bf16 v[80:83], v[132:135], v[228:231], v[80:83]
	v_mfma_f32_16x16x32_bf16 v[72:75], v[140:143], v[228:231], v[72:75]
	v_mfma_f32_16x16x32_bf16 v[104:107], v[168:171], v[184:187], v[104:107]
	v_mfma_f32_16x16x32_bf16 v[96:99], v[176:179], v[184:187], v[96:99]
	v_mfma_f32_16x16x32_bf16 v[92:95], v[168:171], v[198:201], v[92:95]
	v_mfma_f32_16x16x32_bf16 v[88:91], v[176:179], v[198:201], v[88:91]
	v_mfma_f32_16x16x32_bf16 v[84:87], v[168:171], v[216:219], v[84:87]
	v_mfma_f32_16x16x32_bf16 v[76:79], v[176:179], v[216:219], v[76:79]
	v_mfma_f32_16x16x32_bf16 v[68:71], v[168:171], v[224:227], v[68:71]
	v_mfma_f32_16x16x32_bf16 v[64:67], v[176:179], v[224:227], v[64:67]
	v_mfma_f32_16x16x32_bf16 v[104:107], v[172:175], v[188:191], v[104:107]
	v_mfma_f32_16x16x32_bf16 v[96:99], v[180:183], v[188:191], v[96:99]
	v_mfma_f32_16x16x32_bf16 v[92:95], v[172:175], v[202:205], v[92:95]
	v_mfma_f32_16x16x32_bf16 v[88:91], v[180:183], v[202:205], v[88:91]
	v_mfma_f32_16x16x32_bf16 v[84:87], v[172:175], v[220:223], v[84:87]
	v_mfma_f32_16x16x32_bf16 v[76:79], v[180:183], v[220:223], v[76:79]
	v_mfma_f32_16x16x32_bf16 v[68:71], v[172:175], v[228:231], v[68:71]
	v_mfma_f32_16x16x32_bf16 v[64:67], v[180:183], v[228:231], v[64:67]
	s_barrier
; #define PG8_STAGE(bufoff, gbase, voff) do { _Pragma("unroll") for (int _i = 0; _i < 2; ++_i) \
;         __builtin_amdgcn_global_load_lds((const unsigned*)((const char*)(gbase) + (voff)[_i]), (LAS unsigned*)(lds + (bufoff) + ldsw + _i * 8192), 16, 0, 0); } while (0)
; #define PG8_LDA(dst, b, h) do { _Pragma("unroll") for (int m = 0; m < 4; ++m) _Pragma("unroll") for (int k = 0; k < 2; ++k) dst[m][k] = *(const LAS bf16x8*)(lds + PG8_SA(b, h) + aoff + m * 2048 + k * 1024); } while (0)
; #define PG8_MMA(ai, bj, At, Bt) do { __builtin_amdgcn_s_setprio(1); _Pragma("unroll") for (int m = 0; m < 4; ++m) _Pragma("unroll") for (int n = 0; n < 2; ++n) _Pragma("unroll") for (int k = 0; k < 2; ++k) \
;         acc[ai][bj][m][n] = __builtin_amdgcn_mfma_f32_16x16x32_bf16(Bt[n][k], At[m][k], acc[ai][bj][m][n], 0, 0, 0); __builtin_amdgcn_s_setprio(0); } while (0)
; #define PG8_WAIT_V(n) asm volatile("s_waitcnt vmcnt(" #n ")" ::: "memory")
; #define PG8_WAIT_L(n) asm volatile("s_waitcnt lgkmcnt(" #n ")" ::: "memory")
; #define PG8_BAR __builtin_amdgcn_s_barrier()
; #define PG8_SCHED __builtin_amdgcn_sched_barrier(0)
; template <class Epi, bool ALIGN_EPI, bool SP2 = PG8_SP2_DEFAULT>
; __device__ __forceinline__ void gemm_phase(LAS unsigned char* lds, const Gemm g, const StaticOrder& S, const Epi& E) {
;     ...
;         for (int t = 0; t < nt; t += 2) {
;             const bool last = (t == nt - 2);
;             const char* a1 = cA + (size_t)(t + 1) * kstep;
;             const char* a2 = last ? nA : cA + (size_t)(t + 2) * kstep; const char* b2 = last ? nB : cB + (size_t)(t + 2) * kstep;
;             const char* a3 = a2 + kstep; const char* b3 = b2 + kstep;
;     ...
;             PG8_LDA(At, 1, 1); PG8_STAGE(PG8_SB(1, 0), b3, voffB); PG8_STAGE(PG8_SB(1, 1), b3 + hstepB, voffB); PG8_STAGE(PG8_SA(1, 0), a3, voffA);
;             PG8_WAIT_V(8); PG8_WAIT_L(0); PG8_BAR; PG8_MMA(1, 0, At, B0); PG8_MMA(1, 1, At, B1); PG8_BAR; PG8_SCHED;
	s_add_i32 s26, s52, s29
	v_lshl_add_u64 v[160:161], v[160:161], 0, s[4:5]
	s_mov_b32 m0, s26
	ds_read_b128 v[184:187], v167 offset:49152
	ds_read_b128 v[188:191], v167 offset:50176
	ds_read_b128 v[198:201], v167 offset:51200
	ds_read_b128 v[202:205], v167 offset:52224
	ds_read_b128 v[216:219], v167 offset:53248
	ds_read_b128 v[220:223], v167 offset:54272
	ds_read_b128 v[224:227], v167 offset:55296
	ds_read_b128 v[228:231], v167 offset:56320
	global_load_lds_dwordx4 v[160:161], off
	s_add_i32 m0, s26, 0x2000
	s_add_u32 s24, s24, 0x20080
	v_lshl_add_u64 v[160:161], v[192:193], 0, s[4:5]
	s_addc_u32 s25, s25, 0
	s_add_i32 s26, s53, s29
	global_load_lds_dwordx4 v[160:161], off
	v_lshl_add_u64 v[160:161], s[24:25], 0, v[146:147]
	s_mov_b32 m0, s26
	s_nop 0
	global_load_lds_dwordx4 v[160:161], off
	v_lshl_add_u64 v[160:161], s[24:25], 0, v[150:151]
	s_add_i32 m0, s26, 0x2000
	s_nop 0
	global_load_lds_dwordx4 v[160:161], off
	v_lshl_add_u64 v[160:161], v[206:207], 0, s[4:5]
	s_mov_b32 m0, s36
	s_nop 0
	global_load_lds_dwordx4 v[160:161], off
	v_lshl_add_u64 v[160:161], v[210:211], 0, s[4:5]
	s_mov_b32 m0, s37
	s_nop 0
	global_load_lds_dwordx4 v[160:161], off
	s_waitcnt vmcnt(8)
	s_waitcnt lgkmcnt(0)
	s_barrier
	s_waitcnt lgkmcnt(0)
	v_mfma_f32_16x16x32_bf16 v[60:63], v[128:131], v[184:187], v[60:63]
	v_mfma_f32_16x16x32_bf16 v[56:59], v[136:139], v[184:187], v[56:59]
	v_mfma_f32_16x16x32_bf16 v[52:55], v[128:131], v[198:201], v[52:55]
	v_mfma_f32_16x16x32_bf16 v[44:47], v[136:139], v[198:201], v[44:47]
	v_mfma_f32_16x16x32_bf16 v[36:39], v[128:131], v[216:219], v[36:39]
	v_mfma_f32_16x16x32_bf16 v[28:31], v[136:139], v[216:219], v[28:31]
	v_mfma_f32_16x16x32_bf16 v[20:23], v[128:131], v[224:227], v[20:23]
	v_mfma_f32_16x16x32_bf16 v[12:15], v[136:139], v[224:227], v[12:15]
	v_mfma_f32_16x16x32_bf16 v[60:63], v[132:135], v[188:191], v[60:63]
	v_mfma_f32_16x16x32_bf16 v[56:59], v[140:143], v[188:191], v[56:59]
	v_mfma_f32_16x16x32_bf16 v[52:55], v[132:135], v[202:205], v[52:55]
	v_mfma_f32_16x16x32_bf16 v[44:47], v[140:143], v[202:205], v[44:47]
	v_mfma_f32_16x16x32_bf16 v[36:39], v[132:135], v[220:223], v[36:39]
	v_mfma_f32_16x16x32_bf16 v[28:31], v[140:143], v[220:223], v[28:31]
	v_mfma_f32_16x16x32_bf16 v[20:23], v[132:135], v[228:231], v[20:23]
	v_mfma_f32_16x16x32_bf16 v[12:15], v[140:143], v[228:231], v[12:15]
	v_mfma_f32_16x16x32_bf16 v[48:51], v[168:171], v[184:187], v[48:51]
	v_mfma_f32_16x16x32_bf16 v[40:43], v[176:179], v[184:187], v[40:43]
	v_mfma_f32_16x16x32_bf16 v[32:35], v[168:171], v[198:201], v[32:35]
	v_mfma_f32_16x16x32_bf16 v[24:27], v[176:179], v[198:201], v[24:27]
	v_mfma_f32_16x16x32_bf16 v[16:19], v[168:171], v[216:219], v[16:19]
	v_mfma_f32_16x16x32_bf16 v[8:11], v[176:179], v[216:219], v[8:11]
	v_mfma_f32_16x16x32_bf16 v[4:7], v[168:171], v[224:227], v[4:7]
	v_mfma_f32_16x16x32_bf16 v[0:3], v[176:179], v[224:227], v[0:3]
	v_mfma_f32_16x16x32_bf16 v[48:51], v[172:175], v[188:191], v[48:51]
	v_mfma_f32_16x16x32_bf16 v[40:43], v[180:183], v[188:191], v[40:43]
	v_mfma_f32_16x16x32_bf16 v[32:35], v[172:175], v[202:205], v[32:35]
	v_mfma_f32_16x16x32_bf16 v[24:27], v[180:183], v[202:205], v[24:27]
	v_mfma_f32_16x16x32_bf16 v[16:19], v[172:175], v[220:223], v[16:19]
	v_mfma_f32_16x16x32_bf16 v[8:11], v[180:183], v[220:223], v[8:11]
	v_mfma_f32_16x16x32_bf16 v[4:7], v[172:175], v[228:231], v[4:7]
	v_mfma_f32_16x16x32_bf16 v[0:3], v[180:183], v[228:231], v[0:3]
	s_barrier
	s_add_i32 s51, s51, 2
	s_add_u32 s22, s22, 0x100
	s_addc_u32 s23, s23, 0
	s_add_u32 s49, s49, 0x100
	s_addc_u32 s50, s50, 0
	s_cmp_gt_u32 s51, 5
	s_cbranch_scc0 .LBB0_428
	s_and_b64 vcc, exec, s[6:7]
	s_cbranch_vccz .LBB0_431
	s_barrier

; #define PG8_STAGE(bufoff, gbase, voff) do { _Pragma("unroll") for (int _i = 0; _i < 2; ++_i) \
;         __builtin_amdgcn_global_load_lds((const unsigned*)((const char*)(gbase) + (voff)[_i]), (LAS unsigned*)(lds + (bufoff) + ldsw + _i * 8192), 16, 0, 0); } while (0)
; #define PG8_LDA(dst, b, h) do { _Pragma("unroll") for (int m = 0; m < 4; ++m) _Pragma("unroll") for (int k = 0; k < 2; ++k) dst[m][k] = *(const LAS bf16x8*)(lds + PG8_SA(b, h) + aoff + m * 2048 + k * 1024); } while (0)
; #define PG8_LDB(dst, b, h) do { _Pragma("unroll") for (int n = 0; n < 2; ++n) _Pragma("unroll") for (int k = 0; k < 2; ++k) dst[n][k] = *(const LAS bf16x8*)(lds + PG8_SB(b, h) + boff + n * 2048 + k * 1024); } while (0)
; #define PG8_MMA(ai, bj, At, Bt) do { __builtin_amdgcn_s_setprio(1); _Pragma("unroll") for (int m = 0; m < 4; ++m) _Pragma("unroll") for (int n = 0; n < 2; ++n) _Pragma("unroll") for (int k = 0; k < 2; ++k) \
;         acc[ai][bj][m][n] = __builtin_amdgcn_mfma_f32_16x16x32_bf16(Bt[n][k], At[m][k], acc[ai][bj][m][n], 0, 0, 0); __builtin_amdgcn_s_setprio(0); } while (0)
; #define PG8_WAIT_V(n) asm volatile("s_waitcnt vmcnt(" #n ")" ::: "memory")
; #define PG8_WAIT_L(n) asm volatile("s_waitcnt lgkmcnt(" #n ")" ::: "memory")
; #define PG8_BAR __builtin_amdgcn_s_barrier()
; #define PG8_SCHED __builtin_amdgcn_sched_barrier(0)
; template <class Epi, bool ALIGN_EPI, bool SP2 = PG8_SP2_DEFAULT>
; __device__ __forceinline__ void gemm_phase(LAS unsigned char* lds, const Gemm g, const StaticOrder& S, const Epi& E) {
;     ...
;             PG8_LDB(B0, 0, 0); PG8_LDB(B1, 0, 1); PG8_SCHED; PG8_LDA(At, 0, 0); PG8_STAGE(PG8_SA(1, 1), a1 + hstepA, voffA);
;             PG8_WAIT_V(8); PG8_WAIT_L(0); PG8_BAR; PG8_MMA(0, 0, At, B0); PG8_MMA(0, 1, At, B1); PG8_BAR; PG8_SCHED;
;             PG8_LDA(At, 0, 1); PG8_STAGE(PG8_SB(0, 0), b2, voffB); PG8_STAGE(PG8_SB(0, 1), b2 + hstepB, voffB); PG8_STAGE(PG8_SA(0, 0), a2, voffA);
.LBB0_506:
	ds_read_b128 v[144:147], v151
	ds_read_b128 v[156:159], v151 offset:1024
	ds_read_b128 v[160:163], v151 offset:2048
	ds_read_b128 v[164:167], v151 offset:3072
	ds_read_b128 v[168:171], v152
	ds_read_b128 v[172:175], v152 offset:1024
	ds_read_b128 v[176:179], v152 offset:2048
	ds_read_b128 v[180:183], v152 offset:3072
	s_add_u32 s28, s26, 0xfff00080
	s_addc_u32 s29, s27, -1
	s_cmp_eq_u32 s50, 60
	s_cselect_b32 s31, s19, s29
	s_cselect_b32 s30, s25, s28
	s_cselect_b32 s29, s3, s49
	s_cselect_b32 s28, s47, s48
	v_lshl_add_u64 v[192:193], s[26:27], 0, v[136:137]
	s_add_i32 m0, s34, 0xc000
	ds_read_b128 v[184:187], v153
	ds_read_b128 v[188:191], v153 offset:1024
	ds_read_b128 v[198:201], v153 offset:2048
	ds_read_b128 v[202:205], v153 offset:3072
	ds_read_b128 v[216:219], v153 offset:4096
	ds_read_b128 v[220:223], v153 offset:5120
	ds_read_b128 v[224:227], v153 offset:6144
	ds_read_b128 v[228:231], v153 offset:7168
	global_load_lds_dwordx4 v[192:193], off
	v_lshl_add_u64 v[192:193], s[26:27], 0, v[138:139]
	s_add_i32 m0, s34, 0xe000
	s_nop 0
	global_load_lds_dwordx4 v[192:193], off
	s_waitcnt vmcnt(8)
	s_waitcnt lgkmcnt(0)
	s_barrier
	s_waitcnt lgkmcnt(0)
	v_mfma_f32_16x16x32_bf16 v[124:127], v[144:147], v[184:187], v[124:127]
	v_mfma_f32_16x16x32_bf16 v[120:123], v[160:163], v[184:187], v[120:123]
	v_mfma_f32_16x16x32_bf16 v[108:111], v[144:147], v[198:201], v[108:111]
	v_mfma_f32_16x16x32_bf16 v[104:107], v[160:163], v[198:201], v[104:107]
	v_mfma_f32_16x16x32_bf16 v[92:95], v[144:147], v[216:219], v[92:95]
	v_mfma_f32_16x16x32_bf16 v[88:91], v[160:163], v[216:219], v[88:91]
	v_mfma_f32_16x16x32_bf16 v[76:79], v[144:147], v[224:227], v[76:79]
	v_mfma_f32_16x16x32_bf16 v[72:75], v[160:163], v[224:227], v[72:75]
	v_mfma_f32_16x16x32_bf16 v[124:127], v[156:159], v[188:191], v[124:127]
	v_mfma_f32_16x16x32_bf16 v[120:123], v[164:167], v[188:191], v[120:123]
	v_mfma_f32_16x16x32_bf16 v[108:111], v[156:159], v[202:205], v[108:111]
	v_mfma_f32_16x16x32_bf16 v[104:107], v[164:167], v[202:205], v[104:107]
	v_mfma_f32_16x16x32_bf16 v[92:95], v[156:159], v[220:223], v[92:95]
	v_mfma_f32_16x16x32_bf16 v[88:91], v[164:167], v[220:223], v[88:91]
	v_mfma_f32_16x16x32_bf16 v[76:79], v[156:159], v[228:231], v[76:79]
	v_mfma_f32_16x16x32_bf16 v[72:75], v[164:167], v[228:231], v[72:75]
	v_mfma_f32_16x16x32_bf16 v[116:119], v[168:171], v[184:187], v[116:119]
	v_mfma_f32_16x16x32_bf16 v[112:115], v[176:179], v[184:187], v[112:115]
	v_mfma_f32_16x16x32_bf16 v[100:103], v[168:171], v[198:201], v[100:103]
	v_mfma_f32_16x16x32_bf16 v[96:99], v[176:179], v[198:201], v[96:99]
	v_mfma_f32_16x16x32_bf16 v[84:87], v[168:171], v[216:219], v[84:87]
	v_mfma_f32_16x16x32_bf16 v[80:83], v[176:179], v[216:219], v[80:83]
	v_mfma_f32_16x16x32_bf16 v[68:71], v[168:171], v[224:227], v[68:71]
	v_mfma_f32_16x16x32_bf16 v[64:67], v[176:179], v[224:227], v[64:67]
	v_mfma_f32_16x16x32_bf16 v[116:119], v[172:175], v[188:191], v[116:119]
	v_mfma_f32_16x16x32_bf16 v[112:115], v[180:183], v[188:191], v[112:115]
	v_mfma_f32_16x16x32_bf16 v[100:103], v[172:175], v[202:205], v[100:103]
	v_mfma_f32_16x16x32_bf16 v[96:99], v[180:183], v[202:205], v[96:99]
	v_mfma_f32_16x16x32_bf16 v[84:87], v[172:175], v[220:223], v[84:87]
	v_mfma_f32_16x16x32_bf16 v[80:83], v[180:183], v[220:223], v[80:83]
	v_mfma_f32_16x16x32_bf16 v[68:71], v[172:175], v[228:231], v[68:71]
	v_mfma_f32_16x16x32_bf16 v[64:67], v[180:183], v[228:231], v[64:67]
	s_barrier
	s_add_i32 s51, s44, s33
	v_lshl_add_u64 v[192:193], s[28:29], 0, v[130:131]
	s_mov_b32 m0, s51
	ds_read_b128 v[184:187], v153 offset:16384
	ds_read_b128 v[188:191], v153 offset:17408
	ds_read_b128 v[198:201], v153 offset:18432
	ds_read_b128 v[202:205], v153 offset:19456
	ds_read_b128 v[216:219], v153 offset:20480
	ds_read_b128 v[220:223], v153 offset:21504
	ds_read_b128 v[224:227], v153 offset:22528
	ds_read_b128 v[228:231], v153 offset:23552
	global_load_lds_dwordx4 v[192:193], off
	s_add_i32 m0, s51, 0x2000
	s_add_u32 s52, s28, 0x100000
	v_lshl_add_u64 v[206:207], s[28:29], 0, v[134:135]
	s_addc_u32 s53, s29, 0
	s_add_i32 s51, s45, s33
	global_load_lds_dwordx4 v[206:207], off
	v_lshl_add_u64 v[210:211], s[52:53], 0, v[130:131]
	s_mov_b32 m0, s51
	v_lshl_add_u64 v[232:233], s[30:31], 0, v[132:133]
	global_load_lds_dwordx4 v[210:211], off
	v_lshl_add_u64 v[210:211], s[52:53], 0, v[134:135]
	s_add_i32 m0, s51, 0x2000
	s_nop 0
	global_load_lds_dwordx4 v[210:211], off
	v_lshl_add_u64 v[210:211], s[30:31], 0, v[128:129]
	s_mov_b32 m0, s34
	s_nop 0
	global_load_lds_dwordx4 v[210:211], off
	s_mov_b32 m0, s35
	s_nop 0
	global_load_lds_dwordx4 v[232:233], off
	s_waitcnt vmcnt(8)
	s_waitcnt lgkmcnt(0)
	s_barrier
; #define PG8_STAGE(bufoff, gbase, voff) do { _Pragma("unroll") for (int _i = 0; _i < 2; ++_i) \
;         __builtin_amdgcn_global_load_lds((const unsigned*)((const char*)(gbase) + (voff)[_i]), (LAS unsigned*)(lds + (bufoff) + ldsw + _i * 8192), 16, 0, 0); } while (0)
; #define PG8_LDA(dst, b, h) do { _Pragma("unroll") for (int m = 0; m < 4; ++m) _Pragma("unroll") for (int k = 0; k < 2; ++k) dst[m][k] = *(const LAS bf16x8*)(lds + PG8_SA(b, h) + aoff + m * 2048 + k * 1024); } while (0)
; #define PG8_LDB(dst, b, h) do { _Pragma("unroll") for (int n = 0; n < 2; ++n) _Pragma("unroll") for (int k = 0; k < 2; ++k) dst[n][k] = *(const LAS bf16x8*)(lds + PG8_SB(b, h) + boff + n * 2048 + k * 1024); } while (0)
; #define PG8_MMA(ai, bj, At, Bt) do { __builtin_amdgcn_s_setprio(1); _Pragma("unroll") for (int m = 0; m < 4; ++m) _Pragma("unroll") for (int n = 0; n < 2; ++n) _Pragma("unroll") for (int k = 0; k < 2; ++k) \
;         acc[ai][bj][m][n] = __builtin_amdgcn_mfma_f32_16x16x32_bf16(Bt[n][k], At[m][k], acc[ai][bj][m][n], 0, 0, 0); __builtin_amdgcn_s_setprio(0); } while (0)
; #define PG8_WAIT_V(n) asm volatile("s_waitcnt vmcnt(" #n ")" ::: "memory")
; #define PG8_WAIT_L(n) asm volatile("s_waitcnt lgkmcnt(" #n ")" ::: "memory")
; #define PG8_BAR __builtin_amdgcn_s_barrier()
; #define PG8_SCHED __builtin_amdgcn_sched_barrier(0)
; template <class Epi, bool ALIGN_EPI, bool SP2 = PG8_SP2_DEFAULT>
; __device__ __forceinline__ void gemm_phase(LAS unsigned char* lds, const Gemm g, const StaticOrder& S, const Epi& E) {
;     ...
;             PG8_WAIT_V(8); PG8_WAIT_L(0); PG8_BAR; PG8_MMA(1, 0, At, B0); PG8_MMA(1, 1, At, B1); PG8_BAR; PG8_SCHED;
;             PG8_LDB(B0, 1, 0); PG8_LDB(B1, 1, 1); PG8_SCHED; PG8_LDA(At, 1, 0); PG8_STAGE(PG8_SA(0, 1), a2 + hstepA, voffA);
;             PG8_WAIT_V(8); PG8_WAIT_L(0); PG8_BAR; PG8_MMA(0, 0, At, B0); PG8_MMA(0, 1, At, B1); PG8_BAR; PG8_SCHED;
	s_waitcnt lgkmcnt(0)
	v_mfma_f32_16x16x32_bf16 v[60:63], v[144:147], v[184:187], v[60:63]
	v_mfma_f32_16x16x32_bf16 v[56:59], v[160:163], v[184:187], v[56:59]
	v_mfma_f32_16x16x32_bf16 v[44:47], v[144:147], v[198:201], v[44:47]
	v_mfma_f32_16x16x32_bf16 v[40:43], v[160:163], v[198:201], v[40:43]
	v_mfma_f32_16x16x32_bf16 v[28:31], v[144:147], v[216:219], v[28:31]
	v_mfma_f32_16x16x32_bf16 v[24:27], v[160:163], v[216:219], v[24:27]
	v_mfma_f32_16x16x32_bf16 v[12:15], v[144:147], v[224:227], v[12:15]
	v_mfma_f32_16x16x32_bf16 v[8:11], v[160:163], v[224:227], v[8:11]
	v_mfma_f32_16x16x32_bf16 v[60:63], v[156:159], v[188:191], v[60:63]
	v_mfma_f32_16x16x32_bf16 v[56:59], v[164:167], v[188:191], v[56:59]
	v_mfma_f32_16x16x32_bf16 v[44:47], v[156:159], v[202:205], v[44:47]
	v_mfma_f32_16x16x32_bf16 v[40:43], v[164:167], v[202:205], v[40:43]
	v_mfma_f32_16x16x32_bf16 v[28:31], v[156:159], v[220:223], v[28:31]
	v_mfma_f32_16x16x32_bf16 v[24:27], v[164:167], v[220:223], v[24:27]
	v_mfma_f32_16x16x32_bf16 v[12:15], v[156:159], v[228:231], v[12:15]
	v_mfma_f32_16x16x32_bf16 v[8:11], v[164:167], v[228:231], v[8:11]
	v_mfma_f32_16x16x32_bf16 v[52:55], v[168:171], v[184:187], v[52:55]
	v_mfma_f32_16x16x32_bf16 v[48:51], v[176:179], v[184:187], v[48:51]
	v_mfma_f32_16x16x32_bf16 v[36:39], v[168:171], v[198:201], v[36:39]
	v_mfma_f32_16x16x32_bf16 v[32:35], v[176:179], v[198:201], v[32:35]
	v_mfma_f32_16x16x32_bf16 v[20:23], v[168:171], v[216:219], v[20:23]
	v_mfma_f32_16x16x32_bf16 v[16:19], v[176:179], v[216:219], v[16:19]
	v_mfma_f32_16x16x32_bf16 v[4:7], v[168:171], v[224:227], v[4:7]
	v_mfma_f32_16x16x32_bf16 v[0:3], v[176:179], v[224:227], v[0:3]
	v_mfma_f32_16x16x32_bf16 v[52:55], v[172:175], v[188:191], v[52:55]
	v_mfma_f32_16x16x32_bf16 v[48:51], v[180:183], v[188:191], v[48:51]
	v_mfma_f32_16x16x32_bf16 v[36:39], v[172:175], v[202:205], v[36:39]
	v_mfma_f32_16x16x32_bf16 v[32:35], v[180:183], v[202:205], v[32:35]
	v_mfma_f32_16x16x32_bf16 v[20:23], v[172:175], v[220:223], v[20:23]
	v_mfma_f32_16x16x32_bf16 v[16:19], v[180:183], v[220:223], v[16:19]
	v_mfma_f32_16x16x32_bf16 v[4:7], v[172:175], v[228:231], v[4:7]
	v_mfma_f32_16x16x32_bf16 v[0:3], v[180:183], v[228:231], v[0:3]
	s_barrier
	s_add_i32 s51, 0, 0x18000
	v_add_u32_e32 v155, s51, v149
	s_add_i32 s52, 0, 0x1c000
	ds_read_b128 v[144:147], v155
	ds_read_b128 v[156:159], v155 offset:1024
	ds_read_b128 v[160:163], v155 offset:2048
	ds_read_b128 v[164:167], v155 offset:3072
	v_add_u32_e32 v155, s52, v149
	ds_read_b128 v[168:171], v155
	ds_read_b128 v[172:175], v155 offset:1024
	ds_read_b128 v[176:179], v155 offset:2048
	ds_read_b128 v[180:183], v155 offset:3072
	s_add_u32 s30, s30, 0x100000
	s_addc_u32 s31, s31, 0
	s_mov_b32 m0, s36
	v_lshl_add_u64 v[234:235], s[30:31], 0, v[128:129]
	ds_read_b128 v[184:187], v153 offset:32768
	ds_read_b128 v[188:191], v153 offset:33792
	ds_read_b128 v[198:201], v153 offset:34816
	ds_read_b128 v[202:205], v153 offset:35840
	ds_read_b128 v[216:219], v153 offset:36864
	ds_read_b128 v[220:223], v153 offset:37888
	ds_read_b128 v[224:227], v153 offset:38912
	ds_read_b128 v[228:231], v153 offset:39936
	global_load_lds_dwordx4 v[234:235], off
	v_lshl_add_u64 v[234:235], s[30:31], 0, v[132:133]
	s_mov_b32 m0, s37
	s_nop 0
	global_load_lds_dwordx4 v[234:235], off
	s_waitcnt vmcnt(8)
	s_waitcnt lgkmcnt(0)
	s_barrier
	s_waitcnt lgkmcnt(0)
	v_mfma_f32_16x16x32_bf16 v[124:127], v[144:147], v[184:187], v[124:127]
	v_mfma_f32_16x16x32_bf16 v[120:123], v[160:163], v[184:187], v[120:123]
	v_mfma_f32_16x16x32_bf16 v[108:111], v[144:147], v[198:201], v[108:111]
	v_mfma_f32_16x16x32_bf16 v[104:107], v[160:163], v[198:201], v[104:107]
	v_mfma_f32_16x16x32_bf16 v[92:95], v[144:147], v[216:219], v[92:95]
	v_mfma_f32_16x16x32_bf16 v[88:91], v[160:163], v[216:219], v[88:91]
	v_mfma_f32_16x16x32_bf16 v[76:79], v[144:147], v[224:227], v[76:79]
	v_mfma_f32_16x16x32_bf16 v[72:75], v[160:163], v[224:227], v[72:75]
	v_mfma_f32_16x16x32_bf16 v[124:127], v[156:159], v[188:191], v[124:127]
	v_mfma_f32_16x16x32_bf16 v[120:123], v[164:167], v[188:191], v[120:123]
	v_mfma_f32_16x16x32_bf16 v[108:111], v[156:159], v[202:205], v[108:111]
	v_mfma_f32_16x16x32_bf16 v[104:107], v[164:167], v[202:205], v[104:107]
	v_mfma_f32_16x16x32_bf16 v[92:95], v[156:159], v[220:223], v[92:95]
	v_mfma_f32_16x16x32_bf16 v[88:91], v[164:167], v[220:223], v[88:91]
	v_mfma_f32_16x16x32_bf16 v[76:79], v[156:159], v[228:231], v[76:79]
	v_mfma_f32_16x16x32_bf16 v[72:75], v[164:167], v[228:231], v[72:75]
	v_mfma_f32_16x16x32_bf16 v[116:119], v[168:171], v[184:187], v[116:119]
	v_mfma_f32_16x16x32_bf16 v[112:115], v[176:179], v[184:187], v[112:115]
	v_mfma_f32_16x16x32_bf16 v[100:103], v[168:171], v[198:201], v[100:103]
	v_mfma_f32_16x16x32_bf16 v[96:99], v[176:179], v[198:201], v[96:99]
	v_mfma_f32_16x16x32_bf16 v[84:87], v[168:171], v[216:219], v[84:87]
	v_mfma_f32_16x16x32_bf16 v[80:83], v[176:179], v[216:219], v[80:83]
	v_mfma_f32_16x16x32_bf16 v[68:71], v[168:171], v[224:227], v[68:71]
	v_mfma_f32_16x16x32_bf16 v[64:67], v[176:179], v[224:227], v[64:67]
	v_mfma_f32_16x16x32_bf16 v[116:119], v[172:175], v[188:191], v[116:119]
	v_mfma_f32_16x16x32_bf16 v[112:115], v[180:183], v[188:191], v[112:115]
	v_mfma_f32_16x16x32_bf16 v[100:103], v[172:175], v[202:205], v[100:103]
	v_mfma_f32_16x16x32_bf16 v[96:99], v[180:183], v[202:205], v[96:99]
	v_mfma_f32_16x16x32_bf16 v[84:87], v[172:175], v[220:223], v[84:87]
	v_mfma_f32_16x16x32_bf16 v[80:83], v[180:183], v[220:223], v[80:83]
	v_mfma_f32_16x16x32_bf16 v[68:71], v[172:175], v[228:231], v[68:71]
	v_mfma_f32_16x16x32_bf16 v[64:67], v[180:183], v[228:231], v[64:67]
	s_barrier
; #define PG8_STAGE(bufoff, gbase, voff) do { _Pragma("unroll") for (int _i = 0; _i < 2; ++_i) \
;         __builtin_amdgcn_global_load_lds((const unsigned*)((const char*)(gbase) + (voff)[_i]), (LAS unsigned*)(lds + (bufoff) + ldsw + _i * 8192), 16, 0, 0); } while (0)
; #define PG8_LDA(dst, b, h) do { _Pragma("unroll") for (int m = 0; m < 4; ++m) _Pragma("unroll") for (int k = 0; k < 2; ++k) dst[m][k] = *(const LAS bf16x8*)(lds + PG8_SA(b, h) + aoff + m * 2048 + k * 1024); } while (0)
; #define PG8_MMA(ai, bj, At, Bt) do { __builtin_amdgcn_s_setprio(1); _Pragma("unroll") for (int m = 0; m < 4; ++m) _Pragma("unroll") for (int n = 0; n < 2; ++n) _Pragma("unroll") for (int k = 0; k < 2; ++k) \
;         acc[ai][bj][m][n] = __builtin_amdgcn_mfma_f32_16x16x32_bf16(Bt[n][k], At[m][k], acc[ai][bj][m][n], 0, 0, 0); __builtin_amdgcn_s_setprio(0); } while (0)
; #define PG8_WAIT_V(n) asm volatile("s_waitcnt vmcnt(" #n ")" ::: "memory")
; #define PG8_WAIT_L(n) asm volatile("s_waitcnt lgkmcnt(" #n ")" ::: "memory")
; #define PG8_BAR __builtin_amdgcn_s_barrier()
; #define PG8_SCHED __builtin_amdgcn_sched_barrier(0)
; template <class Epi, bool ALIGN_EPI, bool SP2 = PG8_SP2_DEFAULT>
; __device__ __forceinline__ void gemm_phase(LAS unsigned char* lds, const Gemm g, const StaticOrder& S, const Epi& E) {
;     ...
;         for (int t = 0; t < nt; t += 2) {
;             const bool last = (t == nt - 2);
;             const char* a1 = cA + (size_t)(t + 1) * kstep;
;             const char* a2 = last ? nA : cA + (size_t)(t + 2) * kstep; const char* b2 = last ? nB : cB + (size_t)(t + 2) * kstep;
;             const char* a3 = a2 + kstep; const char* b3 = b2 + kstep;
;     ...
;             PG8_LDA(At, 1, 1); PG8_STAGE(PG8_SB(1, 0), b3, voffB); PG8_STAGE(PG8_SB(1, 1), b3 + hstepB, voffB); PG8_STAGE(PG8_SA(1, 0), a3, voffA);
;             PG8_WAIT_V(8); PG8_WAIT_L(0); PG8_BAR; PG8_MMA(1, 0, At, B0); PG8_MMA(1, 1, At, B1); PG8_BAR; PG8_SCHED;
	s_add_i32 s30, s51, s33
	v_lshl_add_u64 v[192:193], v[192:193], 0, s[14:15]
	s_mov_b32 m0, s30
	ds_read_b128 v[184:187], v153 offset:49152
	ds_read_b128 v[188:191], v153 offset:50176
	ds_read_b128 v[198:201], v153 offset:51200
	ds_read_b128 v[202:205], v153 offset:52224
	ds_read_b128 v[216:219], v153 offset:53248
	ds_read_b128 v[220:223], v153 offset:54272
	ds_read_b128 v[224:227], v153 offset:55296
	ds_read_b128 v[228:231], v153 offset:56320
	global_load_lds_dwordx4 v[192:193], off
	s_add_i32 m0, s30, 0x2000
	s_add_u32 s28, s28, 0x100080
	v_lshl_add_u64 v[192:193], v[206:207], 0, s[14:15]
	s_addc_u32 s29, s29, 0
	s_add_i32 s30, s52, s33
	global_load_lds_dwordx4 v[192:193], off
	v_lshl_add_u64 v[192:193], s[28:29], 0, v[130:131]
	s_mov_b32 m0, s30
	s_nop 0
	global_load_lds_dwordx4 v[192:193], off
	v_lshl_add_u64 v[192:193], s[28:29], 0, v[134:135]
	s_add_i32 m0, s30, 0x2000
	s_nop 0
	global_load_lds_dwordx4 v[192:193], off
	v_lshl_add_u64 v[192:193], v[210:211], 0, s[14:15]
	s_mov_b32 m0, s39
	s_nop 0
	global_load_lds_dwordx4 v[192:193], off
	v_lshl_add_u64 v[192:193], v[232:233], 0, s[14:15]
	s_mov_b32 m0, s40
	s_nop 0
	global_load_lds_dwordx4 v[192:193], off
	s_waitcnt vmcnt(8)
	s_waitcnt lgkmcnt(0)
	s_barrier
	s_waitcnt lgkmcnt(0)
	v_mfma_f32_16x16x32_bf16 v[60:63], v[144:147], v[184:187], v[60:63]
	v_mfma_f32_16x16x32_bf16 v[56:59], v[160:163], v[184:187], v[56:59]
	v_mfma_f32_16x16x32_bf16 v[44:47], v[144:147], v[198:201], v[44:47]
	v_mfma_f32_16x16x32_bf16 v[40:43], v[160:163], v[198:201], v[40:43]
	v_mfma_f32_16x16x32_bf16 v[28:31], v[144:147], v[216:219], v[28:31]
	v_mfma_f32_16x16x32_bf16 v[24:27], v[160:163], v[216:219], v[24:27]
	v_mfma_f32_16x16x32_bf16 v[12:15], v[144:147], v[224:227], v[12:15]
	v_mfma_f32_16x16x32_bf16 v[8:11], v[160:163], v[224:227], v[8:11]
	v_mfma_f32_16x16x32_bf16 v[60:63], v[156:159], v[188:191], v[60:63]
	v_mfma_f32_16x16x32_bf16 v[56:59], v[164:167], v[188:191], v[56:59]
	v_mfma_f32_16x16x32_bf16 v[44:47], v[156:159], v[202:205], v[44:47]
	v_mfma_f32_16x16x32_bf16 v[40:43], v[164:167], v[202:205], v[40:43]
	v_mfma_f32_16x16x32_bf16 v[28:31], v[156:159], v[220:223], v[28:31]
	v_mfma_f32_16x16x32_bf16 v[24:27], v[164:167], v[220:223], v[24:27]
	v_mfma_f32_16x16x32_bf16 v[12:15], v[156:159], v[228:231], v[12:15]
	v_mfma_f32_16x16x32_bf16 v[8:11], v[164:167], v[228:231], v[8:11]
	v_mfma_f32_16x16x32_bf16 v[52:55], v[168:171], v[184:187], v[52:55]
	v_mfma_f32_16x16x32_bf16 v[48:51], v[176:179], v[184:187], v[48:51]
	v_mfma_f32_16x16x32_bf16 v[36:39], v[168:171], v[198:201], v[36:39]
	v_mfma_f32_16x16x32_bf16 v[32:35], v[176:179], v[198:201], v[32:35]
	v_mfma_f32_16x16x32_bf16 v[20:23], v[168:171], v[216:219], v[20:23]
	v_mfma_f32_16x16x32_bf16 v[16:19], v[176:179], v[216:219], v[16:19]
	v_mfma_f32_16x16x32_bf16 v[4:7], v[168:171], v[224:227], v[4:7]
	v_mfma_f32_16x16x32_bf16 v[0:3], v[176:179], v[224:227], v[0:3]
	v_mfma_f32_16x16x32_bf16 v[52:55], v[172:175], v[188:191], v[52:55]
	v_mfma_f32_16x16x32_bf16 v[48:51], v[180:183], v[188:191], v[48:51]
	v_mfma_f32_16x16x32_bf16 v[36:39], v[172:175], v[202:205], v[36:39]
	v_mfma_f32_16x16x32_bf16 v[32:35], v[180:183], v[202:205], v[32:35]
	v_mfma_f32_16x16x32_bf16 v[20:23], v[172:175], v[220:223], v[20:23]
	v_mfma_f32_16x16x32_bf16 v[16:19], v[180:183], v[220:223], v[16:19]
	v_mfma_f32_16x16x32_bf16 v[4:7], v[172:175], v[228:231], v[4:7]
	v_mfma_f32_16x16x32_bf16 v[0:3], v[180:183], v[228:231], v[0:3]
	s_barrier
	s_add_i32 s50, s50, 2
	s_add_u32 s26, s26, 0x100
	s_addc_u32 s27, s27, 0
	s_add_u32 s48, s48, 0x100
	s_addc_u32 s49, s49, 0
	s_cmp_gt_u32 s50, 61
	s_cbranch_scc0 .LBB0_506
	s_and_b64 vcc, exec, s[16:17]
	s_cbranch_vccz .LBB0_509
	s_barrier

; #define PG8_STAGE(bufoff, gbase, voff) do { _Pragma("unroll") for (int _i = 0; _i < 2; ++_i) \
;         __builtin_amdgcn_global_load_lds((const unsigned*)((const char*)(gbase) + (voff)[_i]), (LAS unsigned*)(lds + (bufoff) + ldsw + _i * 8192), 16, 0, 0); } while (0)
; #define PG8_LDA(dst, b, h) do { _Pragma("unroll") for (int m = 0; m < 4; ++m) _Pragma("unroll") for (int k = 0; k < 2; ++k) dst[m][k] = *(const LAS bf16x8*)(lds + PG8_SA(b, h) + aoff + m * 2048 + k * 1024); } while (0)
; #define PG8_LDB(dst, b, h) do { _Pragma("unroll") for (int n = 0; n < 2; ++n) _Pragma("unroll") for (int k = 0; k < 2; ++k) dst[n][k] = *(const LAS bf16x8*)(lds + PG8_SB(b, h) + boff + n * 2048 + k * 1024); } while (0)
; #define PG8_MMA(ai, bj, At, Bt) do { __builtin_amdgcn_s_setprio(1); _Pragma("unroll") for (int m = 0; m < 4; ++m) _Pragma("unroll") for (int n = 0; n < 2; ++n) _Pragma("unroll") for (int k = 0; k < 2; ++k) \
;         acc[ai][bj][m][n] = __builtin_amdgcn_mfma_f32_16x16x32_bf16(Bt[n][k], At[m][k], acc[ai][bj][m][n], 0, 0, 0); __builtin_amdgcn_s_setprio(0); } while (0)
; #define PG8_WAIT_V(n) asm volatile("s_waitcnt vmcnt(" #n ")" ::: "memory")
; #define PG8_WAIT_L(n) asm volatile("s_waitcnt lgkmcnt(" #n ")" ::: "memory")
; #define PG8_BAR __builtin_amdgcn_s_barrier()
; #define PG8_SCHED __builtin_amdgcn_sched_barrier(0)
; template <class Epi, bool ALIGN_EPI, bool SP2 = PG8_SP2_DEFAULT>
; __device__ __forceinline__ void gemm_phase(LAS unsigned char* lds, const Gemm g, const StaticOrder& S, const Epi& E) {
;     ...
;             PG8_LDB(B0, 0, 0); PG8_LDB(B1, 0, 1); PG8_SCHED; PG8_LDA(At, 0, 0); PG8_STAGE(PG8_SA(1, 1), a1 + hstepA, voffA);
;             PG8_WAIT_V(8); PG8_WAIT_L(0); PG8_BAR; PG8_MMA(0, 0, At, B0); PG8_MMA(0, 1, At, B1); PG8_BAR; PG8_SCHED;
;             PG8_LDA(At, 0, 1); PG8_STAGE(PG8_SB(0, 0), b2, voffB); PG8_STAGE(PG8_SB(0, 1), b2 + hstepB, voffB); PG8_STAGE(PG8_SA(0, 0), a2, voffA);
.LBB0_598:
	ds_read_b128 v[146:149], v155
	ds_read_b128 v[160:163], v155 offset:1024
	ds_read_b128 v[164:167], v155 offset:2048
	ds_read_b128 v[168:171], v155 offset:3072
	ds_read_b128 v[172:175], v156
	ds_read_b128 v[176:179], v156 offset:1024
	ds_read_b128 v[180:183], v156 offset:2048
	ds_read_b128 v[184:187], v156 offset:3072
	s_add_u32 s24, s22, 0xfff00080
	s_addc_u32 s25, s23, -1
	s_cmp_eq_u32 s47, 60
	s_cselect_b32 s27, s3, s25
	s_cselect_b32 s26, s7, s24
	s_cselect_b32 s25, s9, s45
	s_cselect_b32 s24, s17, s44
	v_lshl_add_u64 v[192:193], s[22:23], 0, v[138:139]
	s_add_i32 m0, s30, 0xc000
	ds_read_b128 v[188:191], v157
	ds_read_b128 v[198:201], v157 offset:1024
	ds_read_b128 v[202:205], v157 offset:2048
	ds_read_b128 v[214:217], v157 offset:3072
	ds_read_b128 v[218:221], v157 offset:4096
	ds_read_b128 v[222:225], v157 offset:5120
	ds_read_b128 v[226:229], v157 offset:6144
	ds_read_b128 v[230:233], v157 offset:7168
	global_load_lds_dwordx4 v[192:193], off
	v_lshl_add_u64 v[192:193], s[22:23], 0, v[140:141]
	s_add_i32 m0, s30, 0xe000
	s_nop 0
	global_load_lds_dwordx4 v[192:193], off
	s_waitcnt vmcnt(8)
	s_waitcnt lgkmcnt(0)
	s_barrier
	s_waitcnt lgkmcnt(0)
	v_mfma_f32_16x16x32_bf16 v[124:127], v[146:149], v[188:191], v[124:127]
	v_mfma_f32_16x16x32_bf16 v[120:123], v[164:167], v[188:191], v[120:123]
	v_mfma_f32_16x16x32_bf16 v[108:111], v[146:149], v[202:205], v[108:111]
	v_mfma_f32_16x16x32_bf16 v[104:107], v[164:167], v[202:205], v[104:107]
	v_mfma_f32_16x16x32_bf16 v[92:95], v[146:149], v[218:221], v[92:95]
	v_mfma_f32_16x16x32_bf16 v[88:91], v[164:167], v[218:221], v[88:91]
	v_mfma_f32_16x16x32_bf16 v[76:79], v[146:149], v[226:229], v[76:79]
	v_mfma_f32_16x16x32_bf16 v[72:75], v[164:167], v[226:229], v[72:75]
	v_mfma_f32_16x16x32_bf16 v[124:127], v[160:163], v[198:201], v[124:127]
	v_mfma_f32_16x16x32_bf16 v[120:123], v[168:171], v[198:201], v[120:123]
	v_mfma_f32_16x16x32_bf16 v[108:111], v[160:163], v[214:217], v[108:111]
	v_mfma_f32_16x16x32_bf16 v[104:107], v[168:171], v[214:217], v[104:107]
	v_mfma_f32_16x16x32_bf16 v[92:95], v[160:163], v[222:225], v[92:95]
	v_mfma_f32_16x16x32_bf16 v[88:91], v[168:171], v[222:225], v[88:91]
	v_mfma_f32_16x16x32_bf16 v[76:79], v[160:163], v[230:233], v[76:79]
	v_mfma_f32_16x16x32_bf16 v[72:75], v[168:171], v[230:233], v[72:75]
	v_mfma_f32_16x16x32_bf16 v[116:119], v[172:175], v[188:191], v[116:119]
	v_mfma_f32_16x16x32_bf16 v[112:115], v[180:183], v[188:191], v[112:115]
	v_mfma_f32_16x16x32_bf16 v[100:103], v[172:175], v[202:205], v[100:103]
	v_mfma_f32_16x16x32_bf16 v[96:99], v[180:183], v[202:205], v[96:99]
	v_mfma_f32_16x16x32_bf16 v[84:87], v[172:175], v[218:221], v[84:87]
	v_mfma_f32_16x16x32_bf16 v[80:83], v[180:183], v[218:221], v[80:83]
	v_mfma_f32_16x16x32_bf16 v[68:71], v[172:175], v[226:229], v[68:71]
	v_mfma_f32_16x16x32_bf16 v[64:67], v[180:183], v[226:229], v[64:67]
	v_mfma_f32_16x16x32_bf16 v[116:119], v[176:179], v[198:201], v[116:119]
	v_mfma_f32_16x16x32_bf16 v[112:115], v[184:187], v[198:201], v[112:115]
	v_mfma_f32_16x16x32_bf16 v[100:103], v[176:179], v[214:217], v[100:103]
	v_mfma_f32_16x16x32_bf16 v[96:99], v[184:187], v[214:217], v[96:99]
	v_mfma_f32_16x16x32_bf16 v[84:87], v[176:179], v[222:225], v[84:87]
	v_mfma_f32_16x16x32_bf16 v[80:83], v[184:187], v[222:225], v[80:83]
	v_mfma_f32_16x16x32_bf16 v[68:71], v[176:179], v[230:233], v[68:71]
	v_mfma_f32_16x16x32_bf16 v[64:67], v[184:187], v[230:233], v[64:67]
	s_barrier
	s_add_i32 s48, s41, s29
	v_lshl_add_u64 v[192:193], s[24:25], 0, v[130:131]
	s_mov_b32 m0, s48
	ds_read_b128 v[188:191], v157 offset:16384
	ds_read_b128 v[198:201], v157 offset:17408
	ds_read_b128 v[202:205], v157 offset:18432
	ds_read_b128 v[214:217], v157 offset:19456
	ds_read_b128 v[218:221], v157 offset:20480
	ds_read_b128 v[222:225], v157 offset:21504
	ds_read_b128 v[226:229], v157 offset:22528
	ds_read_b128 v[230:233], v157 offset:23552
	global_load_lds_dwordx4 v[192:193], off
	s_add_i32 m0, s48, 0x2000
	s_add_u32 s48, s24, 0x100000
	v_lshl_add_u64 v[206:207], s[24:25], 0, v[134:135]
	s_addc_u32 s49, s25, 0
	s_add_i32 s50, s42, s29
	global_load_lds_dwordx4 v[206:207], off
	v_lshl_add_u64 v[210:211], s[48:49], 0, v[130:131]
	s_mov_b32 m0, s50
	v_lshl_add_u64 v[234:235], s[26:27], 0, v[132:133]
	global_load_lds_dwordx4 v[210:211], off
	v_lshl_add_u64 v[210:211], s[48:49], 0, v[134:135]
	s_add_i32 m0, s50, 0x2000
	s_nop 0
	global_load_lds_dwordx4 v[210:211], off
	v_lshl_add_u64 v[210:211], s[26:27], 0, v[128:129]
	s_mov_b32 m0, s30
	s_nop 0
	global_load_lds_dwordx4 v[210:211], off
	s_mov_b32 m0, s31
	s_nop 0
	global_load_lds_dwordx4 v[234:235], off
	s_waitcnt vmcnt(8)
	s_waitcnt lgkmcnt(0)
	s_barrier
; #define PG8_STAGE(bufoff, gbase, voff) do { _Pragma("unroll") for (int _i = 0; _i < 2; ++_i) \
;         __builtin_amdgcn_global_load_lds((const unsigned*)((const char*)(gbase) + (voff)[_i]), (LAS unsigned*)(lds + (bufoff) + ldsw + _i * 8192), 16, 0, 0); } while (0)
; #define PG8_LDA(dst, b, h) do { _Pragma("unroll") for (int m = 0; m < 4; ++m) _Pragma("unroll") for (int k = 0; k < 2; ++k) dst[m][k] = *(const LAS bf16x8*)(lds + PG8_SA(b, h) + aoff + m * 2048 + k * 1024); } while (0)
; #define PG8_LDB(dst, b, h) do { _Pragma("unroll") for (int n = 0; n < 2; ++n) _Pragma("unroll") for (int k = 0; k < 2; ++k) dst[n][k] = *(const LAS bf16x8*)(lds + PG8_SB(b, h) + boff + n * 2048 + k * 1024); } while (0)
; #define PG8_MMA(ai, bj, At, Bt) do { __builtin_amdgcn_s_setprio(1); _Pragma("unroll") for (int m = 0; m < 4; ++m) _Pragma("unroll") for (int n = 0; n < 2; ++n) _Pragma("unroll") for (int k = 0; k < 2; ++k) \
;         acc[ai][bj][m][n] = __builtin_amdgcn_mfma_f32_16x16x32_bf16(Bt[n][k], At[m][k], acc[ai][bj][m][n], 0, 0, 0); __builtin_amdgcn_s_setprio(0); } while (0)
; #define PG8_WAIT_V(n) asm volatile("s_waitcnt vmcnt(" #n ")" ::: "memory")
; #define PG8_WAIT_L(n) asm volatile("s_waitcnt lgkmcnt(" #n ")" ::: "memory")
; #define PG8_BAR __builtin_amdgcn_s_barrier()
; #define PG8_SCHED __builtin_amdgcn_sched_barrier(0)
; template <class Epi, bool ALIGN_EPI, bool SP2 = PG8_SP2_DEFAULT>
; __device__ __forceinline__ void gemm_phase(LAS unsigned char* lds, const Gemm g, const StaticOrder& S, const Epi& E) {
;     ...
;             PG8_WAIT_V(8); PG8_WAIT_L(0); PG8_BAR; PG8_MMA(1, 0, At, B0); PG8_MMA(1, 1, At, B1); PG8_BAR; PG8_SCHED;
;             PG8_LDB(B0, 1, 0); PG8_LDB(B1, 1, 1); PG8_SCHED; PG8_LDA(At, 1, 0); PG8_STAGE(PG8_SA(0, 1), a2 + hstepA, voffA);
;             PG8_WAIT_V(8); PG8_WAIT_L(0); PG8_BAR; PG8_MMA(0, 0, At, B0); PG8_MMA(0, 1, At, B1); PG8_BAR; PG8_SCHED;
	s_waitcnt lgkmcnt(0)
	v_mfma_f32_16x16x32_bf16 v[60:63], v[146:149], v[188:191], v[60:63]
	v_mfma_f32_16x16x32_bf16 v[56:59], v[164:167], v[188:191], v[56:59]
	v_mfma_f32_16x16x32_bf16 v[44:47], v[146:149], v[202:205], v[44:47]
	v_mfma_f32_16x16x32_bf16 v[40:43], v[164:167], v[202:205], v[40:43]
	v_mfma_f32_16x16x32_bf16 v[28:31], v[146:149], v[218:221], v[28:31]
	v_mfma_f32_16x16x32_bf16 v[24:27], v[164:167], v[218:221], v[24:27]
	v_mfma_f32_16x16x32_bf16 v[12:15], v[146:149], v[226:229], v[12:15]
	v_mfma_f32_16x16x32_bf16 v[8:11], v[164:167], v[226:229], v[8:11]
	v_mfma_f32_16x16x32_bf16 v[60:63], v[160:163], v[198:201], v[60:63]
	v_mfma_f32_16x16x32_bf16 v[56:59], v[168:171], v[198:201], v[56:59]
	v_mfma_f32_16x16x32_bf16 v[44:47], v[160:163], v[214:217], v[44:47]
	v_mfma_f32_16x16x32_bf16 v[40:43], v[168:171], v[214:217], v[40:43]
	v_mfma_f32_16x16x32_bf16 v[28:31], v[160:163], v[222:225], v[28:31]
	v_mfma_f32_16x16x32_bf16 v[24:27], v[168:171], v[222:225], v[24:27]
	v_mfma_f32_16x16x32_bf16 v[12:15], v[160:163], v[230:233], v[12:15]
	v_mfma_f32_16x16x32_bf16 v[8:11], v[168:171], v[230:233], v[8:11]
	v_mfma_f32_16x16x32_bf16 v[52:55], v[172:175], v[188:191], v[52:55]
	v_mfma_f32_16x16x32_bf16 v[48:51], v[180:183], v[188:191], v[48:51]
	v_mfma_f32_16x16x32_bf16 v[36:39], v[172:175], v[202:205], v[36:39]
	v_mfma_f32_16x16x32_bf16 v[32:35], v[180:183], v[202:205], v[32:35]
	v_mfma_f32_16x16x32_bf16 v[20:23], v[172:175], v[218:221], v[20:23]
	v_mfma_f32_16x16x32_bf16 v[16:19], v[180:183], v[218:221], v[16:19]
	v_mfma_f32_16x16x32_bf16 v[4:7], v[172:175], v[226:229], v[4:7]
	v_mfma_f32_16x16x32_bf16 v[0:3], v[180:183], v[226:229], v[0:3]
	v_mfma_f32_16x16x32_bf16 v[52:55], v[176:179], v[198:201], v[52:55]
	v_mfma_f32_16x16x32_bf16 v[48:51], v[184:187], v[198:201], v[48:51]
	v_mfma_f32_16x16x32_bf16 v[36:39], v[176:179], v[214:217], v[36:39]
	v_mfma_f32_16x16x32_bf16 v[32:35], v[184:187], v[214:217], v[32:35]
	v_mfma_f32_16x16x32_bf16 v[20:23], v[176:179], v[222:225], v[20:23]
	v_mfma_f32_16x16x32_bf16 v[16:19], v[184:187], v[222:225], v[16:19]
	v_mfma_f32_16x16x32_bf16 v[4:7], v[176:179], v[230:233], v[4:7]
	v_mfma_f32_16x16x32_bf16 v[0:3], v[184:187], v[230:233], v[0:3]
	s_barrier
	s_add_i32 s48, 0, 0x18000
	v_add_u32_e32 v150, s48, v152
	s_add_i32 s49, 0, 0x1c000
	ds_read_b128 v[146:149], v150
	ds_read_b128 v[160:163], v150 offset:1024
	ds_read_b128 v[164:167], v150 offset:2048
	ds_read_b128 v[168:171], v150 offset:3072
	v_add_u32_e32 v150, s49, v152
	ds_read_b128 v[172:175], v150
	ds_read_b128 v[176:179], v150 offset:1024
	ds_read_b128 v[180:183], v150 offset:2048
	ds_read_b128 v[184:187], v150 offset:3072
	s_add_u32 s26, s26, 0x100000
	s_addc_u32 s27, s27, 0
	s_mov_b32 m0, s33
	v_lshl_add_u64 v[236:237], s[26:27], 0, v[128:129]
	ds_read_b128 v[188:191], v157 offset:32768
	ds_read_b128 v[198:201], v157 offset:33792
	ds_read_b128 v[202:205], v157 offset:34816
	ds_read_b128 v[214:217], v157 offset:35840
	ds_read_b128 v[218:221], v157 offset:36864
	ds_read_b128 v[222:225], v157 offset:37888
	ds_read_b128 v[226:229], v157 offset:38912
	ds_read_b128 v[230:233], v157 offset:39936
	global_load_lds_dwordx4 v[236:237], off
	v_lshl_add_u64 v[236:237], s[26:27], 0, v[132:133]
	s_mov_b32 m0, s34
	s_nop 0
	global_load_lds_dwordx4 v[236:237], off
	s_waitcnt vmcnt(8)
	s_waitcnt lgkmcnt(0)
	s_barrier
	s_waitcnt lgkmcnt(0)
	v_mfma_f32_16x16x32_bf16 v[124:127], v[146:149], v[188:191], v[124:127]
	v_mfma_f32_16x16x32_bf16 v[120:123], v[164:167], v[188:191], v[120:123]
	v_mfma_f32_16x16x32_bf16 v[108:111], v[146:149], v[202:205], v[108:111]
	v_mfma_f32_16x16x32_bf16 v[104:107], v[164:167], v[202:205], v[104:107]
	v_mfma_f32_16x16x32_bf16 v[92:95], v[146:149], v[218:221], v[92:95]
	v_mfma_f32_16x16x32_bf16 v[88:91], v[164:167], v[218:221], v[88:91]
	v_mfma_f32_16x16x32_bf16 v[76:79], v[146:149], v[226:229], v[76:79]
	v_mfma_f32_16x16x32_bf16 v[72:75], v[164:167], v[226:229], v[72:75]
	v_mfma_f32_16x16x32_bf16 v[124:127], v[160:163], v[198:201], v[124:127]
	v_mfma_f32_16x16x32_bf16 v[120:123], v[168:171], v[198:201], v[120:123]
	v_mfma_f32_16x16x32_bf16 v[108:111], v[160:163], v[214:217], v[108:111]
	v_mfma_f32_16x16x32_bf16 v[104:107], v[168:171], v[214:217], v[104:107]
	v_mfma_f32_16x16x32_bf16 v[92:95], v[160:163], v[222:225], v[92:95]
	v_mfma_f32_16x16x32_bf16 v[88:91], v[168:171], v[222:225], v[88:91]
	v_mfma_f32_16x16x32_bf16 v[76:79], v[160:163], v[230:233], v[76:79]
	v_mfma_f32_16x16x32_bf16 v[72:75], v[168:171], v[230:233], v[72:75]
	v_mfma_f32_16x16x32_bf16 v[116:119], v[172:175], v[188:191], v[116:119]
	v_mfma_f32_16x16x32_bf16 v[112:115], v[180:183], v[188:191], v[112:115]
	v_mfma_f32_16x16x32_bf16 v[100:103], v[172:175], v[202:205], v[100:103]
	v_mfma_f32_16x16x32_bf16 v[96:99], v[180:183], v[202:205], v[96:99]
	v_mfma_f32_16x16x32_bf16 v[84:87], v[172:175], v[218:221], v[84:87]
	v_mfma_f32_16x16x32_bf16 v[80:83], v[180:183], v[218:221], v[80:83]
	v_mfma_f32_16x16x32_bf16 v[68:71], v[172:175], v[226:229], v[68:71]
	v_mfma_f32_16x16x32_bf16 v[64:67], v[180:183], v[226:229], v[64:67]
	v_mfma_f32_16x16x32_bf16 v[116:119], v[176:179], v[198:201], v[116:119]
	v_mfma_f32_16x16x32_bf16 v[112:115], v[184:187], v[198:201], v[112:115]
	v_mfma_f32_16x16x32_bf16 v[100:103], v[176:179], v[214:217], v[100:103]
	v_mfma_f32_16x16x32_bf16 v[96:99], v[184:187], v[214:217], v[96:99]
	v_mfma_f32_16x16x32_bf16 v[84:87], v[176:179], v[222:225], v[84:87]
	v_mfma_f32_16x16x32_bf16 v[80:83], v[184:187], v[222:225], v[80:83]
	v_mfma_f32_16x16x32_bf16 v[68:71], v[176:179], v[230:233], v[68:71]
	v_mfma_f32_16x16x32_bf16 v[64:67], v[184:187], v[230:233], v[64:67]
	s_barrier
; #define PG8_STAGE(bufoff, gbase, voff) do { _Pragma("unroll") for (int _i = 0; _i < 2; ++_i) \
;         __builtin_amdgcn_global_load_lds((const unsigned*)((const char*)(gbase) + (voff)[_i]), (LAS unsigned*)(lds + (bufoff) + ldsw + _i * 8192), 16, 0, 0); } while (0)
; #define PG8_LDA(dst, b, h) do { _Pragma("unroll") for (int m = 0; m < 4; ++m) _Pragma("unroll") for (int k = 0; k < 2; ++k) dst[m][k] = *(const LAS bf16x8*)(lds + PG8_SA(b, h) + aoff + m * 2048 + k * 1024); } while (0)
; #define PG8_MMA(ai, bj, At, Bt) do { __builtin_amdgcn_s_setprio(1); _Pragma("unroll") for (int m = 0; m < 4; ++m) _Pragma("unroll") for (int n = 0; n < 2; ++n) _Pragma("unroll") for (int k = 0; k < 2; ++k) \
;         acc[ai][bj][m][n] = __builtin_amdgcn_mfma_f32_16x16x32_bf16(Bt[n][k], At[m][k], acc[ai][bj][m][n], 0, 0, 0); __builtin_amdgcn_s_setprio(0); } while (0)
; #define PG8_WAIT_V(n) asm volatile("s_waitcnt vmcnt(" #n ")" ::: "memory")
; #define PG8_WAIT_L(n) asm volatile("s_waitcnt lgkmcnt(" #n ")" ::: "memory")
; #define PG8_BAR __builtin_amdgcn_s_barrier()
; #define PG8_SCHED __builtin_amdgcn_sched_barrier(0)
; template <class Epi, bool ALIGN_EPI, bool SP2 = PG8_SP2_DEFAULT>
; __device__ __forceinline__ void gemm_phase(LAS unsigned char* lds, const Gemm g, const StaticOrder& S, const Epi& E) {
;     ...
;         for (int t = 0; t < nt; t += 2) {
;             const bool last = (t == nt - 2);
;             const char* a1 = cA + (size_t)(t + 1) * kstep;
;             const char* a2 = last ? nA : cA + (size_t)(t + 2) * kstep; const char* b2 = last ? nB : cB + (size_t)(t + 2) * kstep;
;             const char* a3 = a2 + kstep; const char* b3 = b2 + kstep;
;     ...
;             PG8_LDA(At, 1, 1); PG8_STAGE(PG8_SB(1, 0), b3, voffB); PG8_STAGE(PG8_SB(1, 1), b3 + hstepB, voffB); PG8_STAGE(PG8_SA(1, 0), a3, voffA);
;             PG8_WAIT_V(8); PG8_WAIT_L(0); PG8_BAR; PG8_MMA(1, 0, At, B0); PG8_MMA(1, 1, At, B1); PG8_BAR; PG8_SCHED;
	s_add_i32 s26, s48, s29
	v_lshl_add_u64 v[192:193], v[192:193], 0, s[12:13]
	s_mov_b32 m0, s26
	ds_read_b128 v[188:191], v157 offset:49152
	ds_read_b128 v[198:201], v157 offset:50176
	ds_read_b128 v[202:205], v157 offset:51200
	ds_read_b128 v[214:217], v157 offset:52224
	ds_read_b128 v[218:221], v157 offset:53248
	ds_read_b128 v[222:225], v157 offset:54272
	ds_read_b128 v[226:229], v157 offset:55296
	ds_read_b128 v[230:233], v157 offset:56320
	global_load_lds_dwordx4 v[192:193], off
	s_add_i32 m0, s26, 0x2000
	s_add_u32 s24, s24, 0x100080
	v_lshl_add_u64 v[192:193], v[206:207], 0, s[12:13]
	s_addc_u32 s25, s25, 0
	s_add_i32 s26, s49, s29
	global_load_lds_dwordx4 v[192:193], off
	v_lshl_add_u64 v[192:193], s[24:25], 0, v[130:131]
	s_mov_b32 m0, s26
	s_nop 0
	global_load_lds_dwordx4 v[192:193], off
	v_lshl_add_u64 v[192:193], s[24:25], 0, v[134:135]
	s_add_i32 m0, s26, 0x2000
	s_nop 0
	global_load_lds_dwordx4 v[192:193], off
	v_lshl_add_u64 v[192:193], v[210:211], 0, s[12:13]
	s_mov_b32 m0, s36
	s_nop 0
	global_load_lds_dwordx4 v[192:193], off
	v_lshl_add_u64 v[192:193], v[234:235], 0, s[12:13]
	s_mov_b32 m0, s37
	s_nop 0
	global_load_lds_dwordx4 v[192:193], off
	s_waitcnt vmcnt(8)
	s_waitcnt lgkmcnt(0)
	s_barrier
	s_waitcnt lgkmcnt(0)
	v_mfma_f32_16x16x32_bf16 v[60:63], v[146:149], v[188:191], v[60:63]
	v_mfma_f32_16x16x32_bf16 v[56:59], v[164:167], v[188:191], v[56:59]
	v_mfma_f32_16x16x32_bf16 v[44:47], v[146:149], v[202:205], v[44:47]
	v_mfma_f32_16x16x32_bf16 v[40:43], v[164:167], v[202:205], v[40:43]
	v_mfma_f32_16x16x32_bf16 v[28:31], v[146:149], v[218:221], v[28:31]
	v_mfma_f32_16x16x32_bf16 v[24:27], v[164:167], v[218:221], v[24:27]
	v_mfma_f32_16x16x32_bf16 v[12:15], v[146:149], v[226:229], v[12:15]
	v_mfma_f32_16x16x32_bf16 v[8:11], v[164:167], v[226:229], v[8:11]
	v_mfma_f32_16x16x32_bf16 v[60:63], v[160:163], v[198:201], v[60:63]
	v_mfma_f32_16x16x32_bf16 v[56:59], v[168:171], v[198:201], v[56:59]
	v_mfma_f32_16x16x32_bf16 v[44:47], v[160:163], v[214:217], v[44:47]
	v_mfma_f32_16x16x32_bf16 v[40:43], v[168:171], v[214:217], v[40:43]
	v_mfma_f32_16x16x32_bf16 v[28:31], v[160:163], v[222:225], v[28:31]
	v_mfma_f32_16x16x32_bf16 v[24:27], v[168:171], v[222:225], v[24:27]
	v_mfma_f32_16x16x32_bf16 v[12:15], v[160:163], v[230:233], v[12:15]
	v_mfma_f32_16x16x32_bf16 v[8:11], v[168:171], v[230:233], v[8:11]
	v_mfma_f32_16x16x32_bf16 v[52:55], v[172:175], v[188:191], v[52:55]
	v_mfma_f32_16x16x32_bf16 v[48:51], v[180:183], v[188:191], v[48:51]
	v_mfma_f32_16x16x32_bf16 v[36:39], v[172:175], v[202:205], v[36:39]
	v_mfma_f32_16x16x32_bf16 v[32:35], v[180:183], v[202:205], v[32:35]
	v_mfma_f32_16x16x32_bf16 v[20:23], v[172:175], v[218:221], v[20:23]
	v_mfma_f32_16x16x32_bf16 v[16:19], v[180:183], v[218:221], v[16:19]
	v_mfma_f32_16x16x32_bf16 v[4:7], v[172:175], v[226:229], v[4:7]
	v_mfma_f32_16x16x32_bf16 v[0:3], v[180:183], v[226:229], v[0:3]
	v_mfma_f32_16x16x32_bf16 v[52:55], v[176:179], v[198:201], v[52:55]
	v_mfma_f32_16x16x32_bf16 v[48:51], v[184:187], v[198:201], v[48:51]
	v_mfma_f32_16x16x32_bf16 v[36:39], v[176:179], v[214:217], v[36:39]
	v_mfma_f32_16x16x32_bf16 v[32:35], v[184:187], v[214:217], v[32:35]
	v_mfma_f32_16x16x32_bf16 v[20:23], v[176:179], v[222:225], v[20:23]
	v_mfma_f32_16x16x32_bf16 v[16:19], v[184:187], v[222:225], v[16:19]
	v_mfma_f32_16x16x32_bf16 v[4:7], v[176:179], v[230:233], v[4:7]
	v_mfma_f32_16x16x32_bf16 v[0:3], v[184:187], v[230:233], v[0:3]
	s_barrier
	s_add_i32 s47, s47, 2
	s_add_u32 s22, s22, 0x100
	s_addc_u32 s23, s23, 0
	s_add_u32 s44, s44, 0x100
	s_addc_u32 s45, s45, 0
	s_cmp_gt_u32 s47, 61
	s_cbranch_scc0 .LBB0_598
	s_and_b64 vcc, exec, s[14:15]
	s_cbranch_vccz .LBB0_601
	s_barrier

; #define PG8_STAGE(bufoff, gbase, voff) do { _Pragma("unroll") for (int _i = 0; _i < 2; ++_i) \
;         __builtin_amdgcn_global_load_lds((const unsigned*)((const char*)(gbase) + (voff)[_i]), (LAS unsigned*)(lds + (bufoff) + ldsw + _i * 8192), 16, 0, 0); } while (0)
; #define PG8_LDA(dst, b, h) do { _Pragma("unroll") for (int m = 0; m < 4; ++m) _Pragma("unroll") for (int k = 0; k < 2; ++k) dst[m][k] = *(const LAS bf16x8*)(lds + PG8_SA(b, h) + aoff + m * 2048 + k * 1024); } while (0)
; #define PG8_LDB(dst, b, h) do { _Pragma("unroll") for (int n = 0; n < 2; ++n) _Pragma("unroll") for (int k = 0; k < 2; ++k) dst[n][k] = *(const LAS bf16x8*)(lds + PG8_SB(b, h) + boff + n * 2048 + k * 1024); } while (0)
; #define PG8_MMA(ai, bj, At, Bt) do { __builtin_amdgcn_s_setprio(1); _Pragma("unroll") for (int m = 0; m < 4; ++m) _Pragma("unroll") for (int n = 0; n < 2; ++n) _Pragma("unroll") for (int k = 0; k < 2; ++k) \
;         acc[ai][bj][m][n] = __builtin_amdgcn_mfma_f32_16x16x32_bf16(Bt[n][k], At[m][k], acc[ai][bj][m][n], 0, 0, 0); __builtin_amdgcn_s_setprio(0); } while (0)
; #define PG8_WAIT_V(n) asm volatile("s_waitcnt vmcnt(" #n ")" ::: "memory")
; #define PG8_WAIT_L(n) asm volatile("s_waitcnt lgkmcnt(" #n ")" ::: "memory")
; #define PG8_BAR __builtin_amdgcn_s_barrier()
; #define PG8_SCHED __builtin_amdgcn_sched_barrier(0)
; template <class Epi, bool ALIGN_EPI, bool SP2 = PG8_SP2_DEFAULT>
; __device__ __forceinline__ void gemm_phase(LAS unsigned char* lds, const Gemm g, const StaticOrder& S, const Epi& E) {
;     ...
;             PG8_LDB(B0, 0, 0); PG8_LDB(B1, 0, 1); PG8_SCHED; PG8_LDA(At, 0, 0); PG8_STAGE(PG8_SA(1, 1), a1 + hstepA, voffA);
;             PG8_WAIT_V(8); PG8_WAIT_L(0); PG8_BAR; PG8_MMA(0, 0, At, B0); PG8_MMA(0, 1, At, B1); PG8_BAR; PG8_SCHED;
;             PG8_LDA(At, 0, 1); PG8_STAGE(PG8_SB(0, 0), b2, voffB); PG8_STAGE(PG8_SB(0, 1), b2 + hstepB, voffB); PG8_STAGE(PG8_SA(0, 0), a2, voffA);
.LBB0_804:
	ds_read_b128 v[144:147], v153
	ds_read_b128 v[156:159], v153 offset:1024
	ds_read_b128 v[160:163], v153 offset:2048
	ds_read_b128 v[164:167], v153 offset:3072
	ds_read_b128 v[168:171], v154
	ds_read_b128 v[172:175], v154 offset:1024
	ds_read_b128 v[176:179], v154 offset:2048
	ds_read_b128 v[180:183], v154 offset:3072
	s_add_u32 s22, s20, 0x100
	s_addc_u32 s23, s21, 0
	s_cmpk_eq_i32 s49, 0xa8
	s_cselect_b32 s27, s5, s23
	s_cselect_b32 s26, s4, s22
	s_cselect_b32 s25, s19, s48
	s_cselect_b32 s24, s18, s47
	v_lshl_add_u64 v[148:149], s[20:21], 0, v[136:137]
	s_add_i32 m0, s31, 0xc000
	ds_read_b128 v[184:187], v155
	ds_read_b128 v[188:191], v155 offset:1024
	ds_read_b128 v[192:195], v155 offset:2048
	ds_read_b128 v[196:199], v155 offset:3072
	ds_read_b128 v[200:203], v155 offset:4096
	ds_read_b128 v[204:207], v155 offset:5120
	ds_read_b128 v[208:211], v155 offset:6144
	ds_read_b128 v[212:215], v155 offset:7168
	global_load_lds_dwordx4 v[148:149], off
	v_lshl_add_u64 v[148:149], s[20:21], 0, v[138:139]
	s_add_i32 m0, s31, 0xe000
	s_nop 0
	global_load_lds_dwordx4 v[148:149], off
	s_waitcnt vmcnt(8)
	s_waitcnt lgkmcnt(0)
	s_barrier
	s_waitcnt lgkmcnt(0)
	v_mfma_f32_16x16x32_bf16 v[124:127], v[144:147], v[184:187], v[124:127]
	v_mfma_f32_16x16x32_bf16 v[120:123], v[160:163], v[184:187], v[120:123]
	v_mfma_f32_16x16x32_bf16 v[108:111], v[144:147], v[192:195], v[108:111]
	v_mfma_f32_16x16x32_bf16 v[104:107], v[160:163], v[192:195], v[104:107]
	v_mfma_f32_16x16x32_bf16 v[92:95], v[144:147], v[200:203], v[92:95]
	v_mfma_f32_16x16x32_bf16 v[88:91], v[160:163], v[200:203], v[88:91]
	v_mfma_f32_16x16x32_bf16 v[76:79], v[144:147], v[208:211], v[76:79]
	v_mfma_f32_16x16x32_bf16 v[72:75], v[160:163], v[208:211], v[72:75]
	v_mfma_f32_16x16x32_bf16 v[124:127], v[156:159], v[188:191], v[124:127]
	v_mfma_f32_16x16x32_bf16 v[120:123], v[164:167], v[188:191], v[120:123]
	v_mfma_f32_16x16x32_bf16 v[108:111], v[156:159], v[196:199], v[108:111]
	v_mfma_f32_16x16x32_bf16 v[104:107], v[164:167], v[196:199], v[104:107]
	v_mfma_f32_16x16x32_bf16 v[92:95], v[156:159], v[204:207], v[92:95]
	v_mfma_f32_16x16x32_bf16 v[88:91], v[164:167], v[204:207], v[88:91]
	v_mfma_f32_16x16x32_bf16 v[76:79], v[156:159], v[212:215], v[76:79]
	v_mfma_f32_16x16x32_bf16 v[72:75], v[164:167], v[212:215], v[72:75]
	v_mfma_f32_16x16x32_bf16 v[116:119], v[168:171], v[184:187], v[116:119]
	v_mfma_f32_16x16x32_bf16 v[112:115], v[176:179], v[184:187], v[112:115]
	v_mfma_f32_16x16x32_bf16 v[100:103], v[168:171], v[192:195], v[100:103]
	v_mfma_f32_16x16x32_bf16 v[96:99], v[176:179], v[192:195], v[96:99]
	v_mfma_f32_16x16x32_bf16 v[84:87], v[168:171], v[200:203], v[84:87]
	v_mfma_f32_16x16x32_bf16 v[80:83], v[176:179], v[200:203], v[80:83]
	v_mfma_f32_16x16x32_bf16 v[68:71], v[168:171], v[208:211], v[68:71]
	v_mfma_f32_16x16x32_bf16 v[64:67], v[176:179], v[208:211], v[64:67]
	v_mfma_f32_16x16x32_bf16 v[116:119], v[172:175], v[188:191], v[116:119]
	v_mfma_f32_16x16x32_bf16 v[112:115], v[180:183], v[188:191], v[112:115]
	v_mfma_f32_16x16x32_bf16 v[100:103], v[172:175], v[196:199], v[100:103]
	v_mfma_f32_16x16x32_bf16 v[96:99], v[180:183], v[196:199], v[96:99]
	v_mfma_f32_16x16x32_bf16 v[84:87], v[172:175], v[204:207], v[84:87]
	v_mfma_f32_16x16x32_bf16 v[80:83], v[180:183], v[204:207], v[80:83]
	v_mfma_f32_16x16x32_bf16 v[68:71], v[172:175], v[212:215], v[68:71]
	v_mfma_f32_16x16x32_bf16 v[64:67], v[180:183], v[212:215], v[64:67]
	s_barrier
	s_add_i32 s20, s40, s28
	v_lshl_add_u64 v[148:149], s[24:25], 0, v[130:131]
	s_mov_b32 m0, s20
	ds_read_b128 v[184:187], v155 offset:16384
	ds_read_b128 v[188:191], v155 offset:17408
	ds_read_b128 v[192:195], v155 offset:18432
	ds_read_b128 v[196:199], v155 offset:19456
	ds_read_b128 v[200:203], v155 offset:20480
	ds_read_b128 v[204:207], v155 offset:21504
	ds_read_b128 v[208:211], v155 offset:22528
	ds_read_b128 v[212:215], v155 offset:23552
	global_load_lds_dwordx4 v[148:149], off
	s_add_i32 m0, s20, 0x2000
	s_add_u32 s20, s24, 0x2b0000
	v_lshl_add_u64 v[216:217], s[24:25], 0, v[134:135]
	s_addc_u32 s21, s25, 0
	s_add_i32 s50, s41, s28
	global_load_lds_dwordx4 v[216:217], off
	v_lshl_add_u64 v[218:219], s[20:21], 0, v[130:131]
	s_mov_b32 m0, s50
	v_lshl_add_u64 v[220:221], s[26:27], 0, v[132:133]
	global_load_lds_dwordx4 v[218:219], off
	v_lshl_add_u64 v[218:219], s[20:21], 0, v[134:135]
	s_add_i32 m0, s50, 0x2000
	s_nop 0
	global_load_lds_dwordx4 v[218:219], off
	v_lshl_add_u64 v[218:219], s[26:27], 0, v[128:129]
	s_mov_b32 m0, s31
	s_nop 0
	global_load_lds_dwordx4 v[218:219], off
	s_mov_b32 m0, s33
	s_nop 0
	global_load_lds_dwordx4 v[220:221], off
	s_waitcnt vmcnt(8)
	s_waitcnt lgkmcnt(0)
	s_barrier
; #define PG8_STAGE(bufoff, gbase, voff) do { _Pragma("unroll") for (int _i = 0; _i < 2; ++_i) \
;         __builtin_amdgcn_global_load_lds((const unsigned*)((const char*)(gbase) + (voff)[_i]), (LAS unsigned*)(lds + (bufoff) + ldsw + _i * 8192), 16, 0, 0); } while (0)
; #define PG8_LDA(dst, b, h) do { _Pragma("unroll") for (int m = 0; m < 4; ++m) _Pragma("unroll") for (int k = 0; k < 2; ++k) dst[m][k] = *(const LAS bf16x8*)(lds + PG8_SA(b, h) + aoff + m * 2048 + k * 1024); } while (0)
; #define PG8_LDB(dst, b, h) do { _Pragma("unroll") for (int n = 0; n < 2; ++n) _Pragma("unroll") for (int k = 0; k < 2; ++k) dst[n][k] = *(const LAS bf16x8*)(lds + PG8_SB(b, h) + boff + n * 2048 + k * 1024); } while (0)
; #define PG8_MMA(ai, bj, At, Bt) do { __builtin_amdgcn_s_setprio(1); _Pragma("unroll") for (int m = 0; m < 4; ++m) _Pragma("unroll") for (int n = 0; n < 2; ++n) _Pragma("unroll") for (int k = 0; k < 2; ++k) \
;         acc[ai][bj][m][n] = __builtin_amdgcn_mfma_f32_16x16x32_bf16(Bt[n][k], At[m][k], acc[ai][bj][m][n], 0, 0, 0); __builtin_amdgcn_s_setprio(0); } while (0)
; #define PG8_WAIT_V(n) asm volatile("s_waitcnt vmcnt(" #n ")" ::: "memory")
; #define PG8_WAIT_L(n) asm volatile("s_waitcnt lgkmcnt(" #n ")" ::: "memory")
; #define PG8_BAR __builtin_amdgcn_s_barrier()
; #define PG8_SCHED __builtin_amdgcn_sched_barrier(0)
; template <class Epi, bool ALIGN_EPI, bool SP2 = PG8_SP2_DEFAULT>
; __device__ __forceinline__ void gemm_phase(LAS unsigned char* lds, const Gemm g, const StaticOrder& S, const Epi& E) {
;     ...
;             PG8_WAIT_V(8); PG8_WAIT_L(0); PG8_BAR; PG8_MMA(1, 0, At, B0); PG8_MMA(1, 1, At, B1); PG8_BAR; PG8_SCHED;
;             PG8_LDB(B0, 1, 0); PG8_LDB(B1, 1, 1); PG8_SCHED; PG8_LDA(At, 1, 0); PG8_STAGE(PG8_SA(0, 1), a2 + hstepA, voffA);
;             PG8_WAIT_V(8); PG8_WAIT_L(0); PG8_BAR; PG8_MMA(0, 0, At, B0); PG8_MMA(0, 1, At, B1); PG8_BAR; PG8_SCHED;
	s_waitcnt lgkmcnt(0)
	v_mfma_f32_16x16x32_bf16 v[60:63], v[144:147], v[184:187], v[60:63]
	v_mfma_f32_16x16x32_bf16 v[56:59], v[160:163], v[184:187], v[56:59]
	v_mfma_f32_16x16x32_bf16 v[44:47], v[144:147], v[192:195], v[44:47]
	v_mfma_f32_16x16x32_bf16 v[40:43], v[160:163], v[192:195], v[40:43]
	v_mfma_f32_16x16x32_bf16 v[28:31], v[144:147], v[200:203], v[28:31]
	v_mfma_f32_16x16x32_bf16 v[24:27], v[160:163], v[200:203], v[24:27]
	v_mfma_f32_16x16x32_bf16 v[12:15], v[144:147], v[208:211], v[12:15]
	v_mfma_f32_16x16x32_bf16 v[8:11], v[160:163], v[208:211], v[8:11]
	v_mfma_f32_16x16x32_bf16 v[60:63], v[156:159], v[188:191], v[60:63]
	v_mfma_f32_16x16x32_bf16 v[56:59], v[164:167], v[188:191], v[56:59]
	v_mfma_f32_16x16x32_bf16 v[44:47], v[156:159], v[196:199], v[44:47]
	v_mfma_f32_16x16x32_bf16 v[40:43], v[164:167], v[196:199], v[40:43]
	v_mfma_f32_16x16x32_bf16 v[28:31], v[156:159], v[204:207], v[28:31]
	v_mfma_f32_16x16x32_bf16 v[24:27], v[164:167], v[204:207], v[24:27]
	v_mfma_f32_16x16x32_bf16 v[12:15], v[156:159], v[212:215], v[12:15]
	v_mfma_f32_16x16x32_bf16 v[8:11], v[164:167], v[212:215], v[8:11]
	v_mfma_f32_16x16x32_bf16 v[52:55], v[168:171], v[184:187], v[52:55]
	v_mfma_f32_16x16x32_bf16 v[48:51], v[176:179], v[184:187], v[48:51]
	v_mfma_f32_16x16x32_bf16 v[36:39], v[168:171], v[192:195], v[36:39]
	v_mfma_f32_16x16x32_bf16 v[32:35], v[176:179], v[192:195], v[32:35]
	v_mfma_f32_16x16x32_bf16 v[20:23], v[168:171], v[200:203], v[20:23]
	v_mfma_f32_16x16x32_bf16 v[16:19], v[176:179], v[200:203], v[16:19]
	v_mfma_f32_16x16x32_bf16 v[4:7], v[168:171], v[208:211], v[4:7]
	v_mfma_f32_16x16x32_bf16 v[0:3], v[176:179], v[208:211], v[0:3]
	v_mfma_f32_16x16x32_bf16 v[52:55], v[172:175], v[188:191], v[52:55]
	v_mfma_f32_16x16x32_bf16 v[48:51], v[180:183], v[188:191], v[48:51]
	v_mfma_f32_16x16x32_bf16 v[36:39], v[172:175], v[196:199], v[36:39]
	v_mfma_f32_16x16x32_bf16 v[32:35], v[180:183], v[196:199], v[32:35]
	v_mfma_f32_16x16x32_bf16 v[20:23], v[172:175], v[204:207], v[20:23]
	v_mfma_f32_16x16x32_bf16 v[16:19], v[180:183], v[204:207], v[16:19]
	v_mfma_f32_16x16x32_bf16 v[4:7], v[172:175], v[212:215], v[4:7]
	v_mfma_f32_16x16x32_bf16 v[0:3], v[180:183], v[212:215], v[0:3]
	s_barrier
	s_add_i32 s50, 0, 0x18000
	s_add_i32 s51, 0, 0x1c000
	v_add_u32_e32 v164, s50, v151
	v_add_u32_e32 v180, s51, v151
	ds_read_b128 v[144:147], v164
	ds_read_b128 v[156:159], v164 offset:1024
	ds_read_b128 v[160:163], v164 offset:2048
	ds_read_b128 v[164:167], v164 offset:3072
	ds_read_b128 v[168:171], v180
	ds_read_b128 v[172:175], v180 offset:1024
	ds_read_b128 v[176:179], v180 offset:2048
	ds_read_b128 v[180:183], v180 offset:3072
	s_add_u32 s20, s26, 0x2b0000
	s_addc_u32 s21, s27, 0
	s_mov_b32 m0, s34
	v_lshl_add_u64 v[222:223], s[20:21], 0, v[128:129]
	ds_read_b128 v[184:187], v155 offset:32768
	ds_read_b128 v[188:191], v155 offset:33792
	ds_read_b128 v[192:195], v155 offset:34816
	ds_read_b128 v[196:199], v155 offset:35840
	ds_read_b128 v[200:203], v155 offset:36864
	ds_read_b128 v[204:207], v155 offset:37888
	ds_read_b128 v[208:211], v155 offset:38912
	ds_read_b128 v[212:215], v155 offset:39936
	global_load_lds_dwordx4 v[222:223], off
	v_lshl_add_u64 v[222:223], s[20:21], 0, v[132:133]
	s_mov_b32 m0, s35
	s_nop 0
	global_load_lds_dwordx4 v[222:223], off
	s_waitcnt vmcnt(8)
	s_waitcnt lgkmcnt(0)
	s_barrier
	s_waitcnt lgkmcnt(0)
	v_mfma_f32_16x16x32_bf16 v[124:127], v[144:147], v[184:187], v[124:127]
	v_mfma_f32_16x16x32_bf16 v[120:123], v[160:163], v[184:187], v[120:123]
	v_mfma_f32_16x16x32_bf16 v[108:111], v[144:147], v[192:195], v[108:111]
	v_mfma_f32_16x16x32_bf16 v[104:107], v[160:163], v[192:195], v[104:107]
	v_mfma_f32_16x16x32_bf16 v[92:95], v[144:147], v[200:203], v[92:95]
	v_mfma_f32_16x16x32_bf16 v[88:91], v[160:163], v[200:203], v[88:91]
	v_mfma_f32_16x16x32_bf16 v[76:79], v[144:147], v[208:211], v[76:79]
	v_mfma_f32_16x16x32_bf16 v[72:75], v[160:163], v[208:211], v[72:75]
	v_mfma_f32_16x16x32_bf16 v[124:127], v[156:159], v[188:191], v[124:127]
	v_mfma_f32_16x16x32_bf16 v[120:123], v[164:167], v[188:191], v[120:123]
	v_mfma_f32_16x16x32_bf16 v[108:111], v[156:159], v[196:199], v[108:111]
	v_mfma_f32_16x16x32_bf16 v[104:107], v[164:167], v[196:199], v[104:107]
	v_mfma_f32_16x16x32_bf16 v[92:95], v[156:159], v[204:207], v[92:95]
	v_mfma_f32_16x16x32_bf16 v[88:91], v[164:167], v[204:207], v[88:91]
	v_mfma_f32_16x16x32_bf16 v[76:79], v[156:159], v[212:215], v[76:79]
	v_mfma_f32_16x16x32_bf16 v[72:75], v[164:167], v[212:215], v[72:75]
	v_mfma_f32_16x16x32_bf16 v[116:119], v[168:171], v[184:187], v[116:119]
	v_mfma_f32_16x16x32_bf16 v[112:115], v[176:179], v[184:187], v[112:115]
	v_mfma_f32_16x16x32_bf16 v[100:103], v[168:171], v[192:195], v[100:103]
	v_mfma_f32_16x16x32_bf16 v[96:99], v[176:179], v[192:195], v[96:99]
	v_mfma_f32_16x16x32_bf16 v[84:87], v[168:171], v[200:203], v[84:87]
	v_mfma_f32_16x16x32_bf16 v[80:83], v[176:179], v[200:203], v[80:83]
	v_mfma_f32_16x16x32_bf16 v[68:71], v[168:171], v[208:211], v[68:71]
	v_mfma_f32_16x16x32_bf16 v[64:67], v[176:179], v[208:211], v[64:67]
	v_mfma_f32_16x16x32_bf16 v[116:119], v[172:175], v[188:191], v[116:119]
	v_mfma_f32_16x16x32_bf16 v[112:115], v[180:183], v[188:191], v[112:115]
	v_mfma_f32_16x16x32_bf16 v[100:103], v[172:175], v[196:199], v[100:103]
	v_mfma_f32_16x16x32_bf16 v[96:99], v[180:183], v[196:199], v[96:99]
	v_mfma_f32_16x16x32_bf16 v[84:87], v[172:175], v[204:207], v[84:87]
	v_mfma_f32_16x16x32_bf16 v[80:83], v[180:183], v[204:207], v[80:83]
	v_mfma_f32_16x16x32_bf16 v[68:71], v[172:175], v[212:215], v[68:71]
	v_mfma_f32_16x16x32_bf16 v[64:67], v[180:183], v[212:215], v[64:67]
	s_barrier
; #define PG8_STAGE(bufoff, gbase, voff) do { _Pragma("unroll") for (int _i = 0; _i < 2; ++_i) \
;         __builtin_amdgcn_global_load_lds((const unsigned*)((const char*)(gbase) + (voff)[_i]), (LAS unsigned*)(lds + (bufoff) + ldsw + _i * 8192), 16, 0, 0); } while (0)
; #define PG8_LDA(dst, b, h) do { _Pragma("unroll") for (int m = 0; m < 4; ++m) _Pragma("unroll") for (int k = 0; k < 2; ++k) dst[m][k] = *(const LAS bf16x8*)(lds + PG8_SA(b, h) + aoff + m * 2048 + k * 1024); } while (0)
; #define PG8_MMA(ai, bj, At, Bt) do { __builtin_amdgcn_s_setprio(1); _Pragma("unroll") for (int m = 0; m < 4; ++m) _Pragma("unroll") for (int n = 0; n < 2; ++n) _Pragma("unroll") for (int k = 0; k < 2; ++k) \
;         acc[ai][bj][m][n] = __builtin_amdgcn_mfma_f32_16x16x32_bf16(Bt[n][k], At[m][k], acc[ai][bj][m][n], 0, 0, 0); __builtin_amdgcn_s_setprio(0); } while (0)
; #define PG8_WAIT_V(n) asm volatile("s_waitcnt vmcnt(" #n ")" ::: "memory")
; #define PG8_WAIT_L(n) asm volatile("s_waitcnt lgkmcnt(" #n ")" ::: "memory")
; #define PG8_BAR __builtin_amdgcn_s_barrier()
; #define PG8_SCHED __builtin_amdgcn_sched_barrier(0)
; template <class Epi, bool ALIGN_EPI, bool SP2 = PG8_SP2_DEFAULT>
; __device__ __forceinline__ void gemm_phase(LAS unsigned char* lds, const Gemm g, const StaticOrder& S, const Epi& E) {
;     ...
;         for (int t = 0; t < nt; t += 2) {
;             const bool last = (t == nt - 2);
;             const char* a1 = cA + (size_t)(t + 1) * kstep;
;             const char* a2 = last ? nA : cA + (size_t)(t + 2) * kstep; const char* b2 = last ? nB : cB + (size_t)(t + 2) * kstep;
;             const char* a3 = a2 + kstep; const char* b3 = b2 + kstep;
;     ...
;             PG8_LDA(At, 1, 1); PG8_STAGE(PG8_SB(1, 0), b3, voffB); PG8_STAGE(PG8_SB(1, 1), b3 + hstepB, voffB); PG8_STAGE(PG8_SA(1, 0), a3, voffA);
;             PG8_WAIT_V(8); PG8_WAIT_L(0); PG8_BAR; PG8_MMA(1, 0, At, B0); PG8_MMA(1, 1, At, B1); PG8_BAR; PG8_SCHED;
	s_add_i32 s20, s50, s28
	v_lshl_add_u64 v[148:149], v[148:149], 0, s[6:7]
	s_mov_b32 m0, s20
	ds_read_b128 v[184:187], v155 offset:49152
	ds_read_b128 v[188:191], v155 offset:50176
	ds_read_b128 v[192:195], v155 offset:51200
	ds_read_b128 v[196:199], v155 offset:52224
	ds_read_b128 v[200:203], v155 offset:53248
	ds_read_b128 v[204:207], v155 offset:54272
	ds_read_b128 v[208:211], v155 offset:55296
	ds_read_b128 v[212:215], v155 offset:56320
	global_load_lds_dwordx4 v[148:149], off
	s_add_i32 m0, s20, 0x2000
	s_add_u32 s20, s24, 0x2b0080
	v_lshl_add_u64 v[148:149], v[216:217], 0, s[6:7]
	s_addc_u32 s21, s25, 0
	s_add_i32 s24, s51, s28
	global_load_lds_dwordx4 v[148:149], off
	v_lshl_add_u64 v[148:149], s[20:21], 0, v[130:131]
	s_mov_b32 m0, s24
	s_nop 0
	global_load_lds_dwordx4 v[148:149], off
	v_lshl_add_u64 v[148:149], s[20:21], 0, v[134:135]
	s_add_i32 m0, s24, 0x2000
	s_nop 0
	global_load_lds_dwordx4 v[148:149], off
	v_lshl_add_u64 v[148:149], v[218:219], 0, s[6:7]
	s_mov_b32 m0, s37
	s_nop 0
	global_load_lds_dwordx4 v[148:149], off
	v_lshl_add_u64 v[148:149], v[220:221], 0, s[6:7]
	s_mov_b32 m0, s38
	s_nop 0
	global_load_lds_dwordx4 v[148:149], off
	s_waitcnt vmcnt(8)
	s_waitcnt lgkmcnt(0)
	s_barrier
	s_waitcnt lgkmcnt(0)
	v_mfma_f32_16x16x32_bf16 v[60:63], v[144:147], v[184:187], v[60:63]
	v_mfma_f32_16x16x32_bf16 v[56:59], v[160:163], v[184:187], v[56:59]
	v_mfma_f32_16x16x32_bf16 v[44:47], v[144:147], v[192:195], v[44:47]
	v_mfma_f32_16x16x32_bf16 v[40:43], v[160:163], v[192:195], v[40:43]
	v_mfma_f32_16x16x32_bf16 v[28:31], v[144:147], v[200:203], v[28:31]
	v_mfma_f32_16x16x32_bf16 v[24:27], v[160:163], v[200:203], v[24:27]
	v_mfma_f32_16x16x32_bf16 v[12:15], v[144:147], v[208:211], v[12:15]
	v_mfma_f32_16x16x32_bf16 v[8:11], v[160:163], v[208:211], v[8:11]
	v_mfma_f32_16x16x32_bf16 v[60:63], v[156:159], v[188:191], v[60:63]
	v_mfma_f32_16x16x32_bf16 v[56:59], v[164:167], v[188:191], v[56:59]
	v_mfma_f32_16x16x32_bf16 v[44:47], v[156:159], v[196:199], v[44:47]
	v_mfma_f32_16x16x32_bf16 v[40:43], v[164:167], v[196:199], v[40:43]
	v_mfma_f32_16x16x32_bf16 v[28:31], v[156:159], v[204:207], v[28:31]
	v_mfma_f32_16x16x32_bf16 v[24:27], v[164:167], v[204:207], v[24:27]
	v_mfma_f32_16x16x32_bf16 v[12:15], v[156:159], v[212:215], v[12:15]
	v_mfma_f32_16x16x32_bf16 v[8:11], v[164:167], v[212:215], v[8:11]
	v_mfma_f32_16x16x32_bf16 v[52:55], v[168:171], v[184:187], v[52:55]
	v_mfma_f32_16x16x32_bf16 v[48:51], v[176:179], v[184:187], v[48:51]
	v_mfma_f32_16x16x32_bf16 v[36:39], v[168:171], v[192:195], v[36:39]
	v_mfma_f32_16x16x32_bf16 v[32:35], v[176:179], v[192:195], v[32:35]
	v_mfma_f32_16x16x32_bf16 v[20:23], v[168:171], v[200:203], v[20:23]
	v_mfma_f32_16x16x32_bf16 v[16:19], v[176:179], v[200:203], v[16:19]
	v_mfma_f32_16x16x32_bf16 v[4:7], v[168:171], v[208:211], v[4:7]
	v_mfma_f32_16x16x32_bf16 v[0:3], v[176:179], v[208:211], v[0:3]
	v_mfma_f32_16x16x32_bf16 v[52:55], v[172:175], v[188:191], v[52:55]
	v_mfma_f32_16x16x32_bf16 v[48:51], v[180:183], v[188:191], v[48:51]
	v_mfma_f32_16x16x32_bf16 v[36:39], v[172:175], v[196:199], v[36:39]
	v_mfma_f32_16x16x32_bf16 v[32:35], v[180:183], v[196:199], v[32:35]
	v_mfma_f32_16x16x32_bf16 v[20:23], v[172:175], v[204:207], v[20:23]
	v_mfma_f32_16x16x32_bf16 v[16:19], v[180:183], v[204:207], v[16:19]
	v_mfma_f32_16x16x32_bf16 v[4:7], v[172:175], v[212:215], v[4:7]
	v_mfma_f32_16x16x32_bf16 v[0:3], v[180:183], v[212:215], v[0:3]
	s_barrier
	s_add_i32 s49, s49, 2
	s_add_u32 s47, s47, 0x100
	s_addc_u32 s48, s48, 0
	s_cmpk_gt_u32 s49, 0xa9
	s_mov_b64 s[20:21], s[22:23]
	s_cbranch_scc0 .LBB0_804
	s_and_b64 vcc, exec, s[8:9]
	s_cbranch_vccz .LBB0_807
	s_barrier
